# GEMM unit loops no longer drain vmcnt after the epilogue stores before starting the next unit
# speedup vs baseline: 1.0105x; 1.0071x over previous
;     DI void operator()(const f32x4 (&acc)[2][2][4][2], const Unit& u, int wr, int wc, int fr, int fq) const {
;         float* hp = h_c + (size_t)(u.pm * BM) * D;
;         const float* g = gate + (size_t)8 * (6 * D);
;         const int col0 = u.pn * BM + wc * 32 + 4 * fq;
;         f32x4 gv[2][2];
; #pragma unroll
;         for (int bj = 0; bj < 2; ++bj)
; #pragma unroll
;             for (int n = 0; n < 2; ++n) gv[bj][n] = *(const f32x4*)(g + col0 + bj * HALF + n * 16);
; #pragma unroll
;         for (int ai = 0; ai < 2; ++ai)
; #pragma unroll
;             for (int m = 0; m < 4; ++m) { float* rp = hp + (size_t)(wr * 64 + fr + ai * HALF + m * 16) * D + col0;
; #pragma unroll
;                 for (int bj = 0; bj < 2; ++bj)
; #pragma unroll
;                     for (int n = 0; n < 2; ++n) { const f32x4 v = gv[bj][n] * acc[ai][bj][m][n];
; #pragma unroll
;                         for (int j = 0; j < 4; ++j) __hip_atomic_fetch_add(rp + bj * HALF + n * 16 + j, v[j], __ATOMIC_RELAXED, __HIP_MEMORY_SCOPE_AGENT); } }
.LBB0_41:
	v_mov_b32_e32 v158, v155
	v_mov_b32_e32 v130, v154
	s_lshl_b32 s6, s31, 8
	s_or_b32 s6, s6, s83
	v_lshl_add_u32 v130, v130, 2, s6
	v_ashrrev_i32_e32 v131, 31, v130
	v_lshlrev_b64 v[152:153], 2, v[130:131]
	v_lshl_add_u64 v[130:131], s[52:53], 0, v[152:153]
	global_load_dwordx4 v[142:145], v[130:131], off
	global_load_dwordx4 v[138:141], v[130:131], off offset:64
	global_load_dwordx4 v[134:137], v[130:131], off offset:512
	s_nop 0
	global_load_dwordx4 v[130:133], v[130:131], off offset:576
	s_lshl_b32 s6, s30, 8
	s_ashr_i32 s7, s6, 31
	s_lshl_b64 s[6:7], s[6:7], 13
	v_add_u32_e32 v158, s41, v158
	s_add_u32 s6, s38, s6
	v_ashrrev_i32_e32 v159, 31, v158
	s_addc_u32 s7, s39, s7
	v_lshlrev_b64 v[158:159], 13, v[158:159]
	v_lshl_add_u64 v[152:153], s[6:7], 0, v[152:153]
	v_lshl_add_u64 v[152:153], v[152:153], 0, v[158:159]
	s_mov_b64 s[6:7], 0x20000
	s_mov_b32 s3, 0x20000
	v_lshl_add_u64 v[158:159], v[152:153], 0, s[6:7]
	v_add_co_u32_e32 v160, vcc, s3, v152
	s_mov_b64 s[6:7], 0x40000
	s_nop 0
	v_addc_co_u32_e32 v161, vcc, 0, v153, vcc
	v_lshl_add_u64 v[162:163], v[152:153], 0, s[6:7]
	s_mov_b32 s6, 0x40000
	v_add_co_u32_e32 v164, vcc, s6, v152
	s_mov_b64 s[6:7], 0x60000
	s_nop 0
	v_addc_co_u32_e32 v165, vcc, 0, v153, vcc
	v_lshl_add_u64 v[168:169], v[152:153], 0, s[6:7]
	s_mov_b32 s6, 0x60000
	v_add_co_u32_e32 v170, vcc, s6, v152
	s_mov_b64 s[6:7], 0x100000
	s_nop 0
	v_addc_co_u32_e32 v171, vcc, 0, v153, vcc
	s_mov_b32 s31, s86
	s_mov_b32 s30, s87
	s_mov_b64 s[56:57], s[46:47]
	s_mov_b64 s[54:55], s[44:45]
	s_waitcnt vmcnt(0)
	v_mul_f32_e32 v126, v126, v142
	v_mul_f32_e32 v76, v76, v142
	v_mul_f32_e32 v127, v127, v143
	v_mul_f32_e32 v128, v128, v144
	v_mul_f32_e32 v129, v129, v145
	v_mul_f32_e32 v122, v122, v138
	v_mul_f32_e32 v123, v123, v139
	v_mul_f32_e32 v124, v124, v140
	v_mul_f32_e32 v125, v125, v141
	v_mul_f32_e32 v118, v118, v134
	v_mul_f32_e32 v119, v119, v135
	v_mul_f32_e32 v120, v120, v136
	v_mul_f32_e32 v121, v121, v137
	v_mul_f32_e32 v114, v114, v130
	v_mul_f32_e32 v115, v115, v131
	v_mul_f32_e32 v116, v116, v132
	v_mul_f32_e32 v117, v117, v133
	v_mul_f32_e32 v110, v110, v142
	v_mul_f32_e32 v111, v111, v143
	v_mul_f32_e32 v112, v112, v144
	v_mul_f32_e32 v113, v113, v145
	v_mul_f32_e32 v106, v106, v138
	v_mul_f32_e32 v107, v107, v139
	v_mul_f32_e32 v108, v108, v140
	v_mul_f32_e32 v109, v109, v141
	v_mul_f32_e32 v102, v102, v134
	v_mul_f32_e32 v103, v103, v135
	v_mul_f32_e32 v104, v104, v136
	v_mul_f32_e32 v105, v105, v137
	v_mul_f32_e32 v98, v98, v130
	v_mul_f32_e32 v99, v99, v131
	v_mul_f32_e32 v100, v100, v132
	v_mul_f32_e32 v101, v101, v133
	v_mul_f32_e32 v92, v92, v142
	v_mul_f32_e32 v93, v93, v143
	v_mul_f32_e32 v94, v94, v144
	v_mul_f32_e32 v95, v95, v145
	v_mul_f32_e32 v88, v88, v138
	v_mul_f32_e32 v89, v89, v139
	v_mul_f32_e32 v90, v90, v140
	v_mul_f32_e32 v91, v91, v141
	v_mul_f32_e32 v84, v84, v134
	v_mul_f32_e32 v85, v85, v135
	v_mul_f32_e32 v86, v86, v136
	v_mul_f32_e32 v87, v87, v137
	v_mul_f32_e32 v80, v80, v130
	v_mul_f32_e32 v81, v81, v131
	v_mul_f32_e32 v82, v82, v132
	v_mul_f32_e32 v83, v83, v133
	global_atomic_add_f32 v[152:153], v126, off
	global_atomic_add_f32 v[152:153], v127, off offset:4
	global_atomic_add_f32 v[152:153], v128, off offset:8
	global_atomic_add_f32 v[152:153], v129, off offset:12
	global_atomic_add_f32 v[152:153], v122, off offset:64
	global_atomic_add_f32 v[152:153], v123, off offset:68
	global_atomic_add_f32 v[152:153], v124, off offset:72
	global_atomic_add_f32 v[152:153], v125, off offset:76
	global_atomic_add_f32 v[152:153], v118, off offset:512
	global_atomic_add_f32 v[152:153], v119, off offset:516
	global_atomic_add_f32 v[152:153], v120, off offset:520
	global_atomic_add_f32 v[152:153], v121, off offset:524
	global_atomic_add_f32 v[152:153], v114, off offset:576
	global_atomic_add_f32 v[152:153], v115, off offset:580
	global_atomic_add_f32 v[152:153], v116, off offset:584
	global_atomic_add_f32 v[152:153], v117, off offset:588
	global_atomic_add_f32 v[160:161], v110, off
	global_atomic_add_f32 v[158:159], v111, off offset:4
	global_atomic_add_f32 v[158:159], v112, off offset:8
	global_atomic_add_f32 v[158:159], v113, off offset:12
	global_atomic_add_f32 v[158:159], v106, off offset:64
	global_atomic_add_f32 v[158:159], v107, off offset:68
	global_atomic_add_f32 v[158:159], v108, off offset:72
	global_atomic_add_f32 v[158:159], v109, off offset:76
	global_atomic_add_f32 v[158:159], v102, off offset:512
	global_atomic_add_f32 v[158:159], v103, off offset:516
	global_atomic_add_f32 v[158:159], v104, off offset:520
	global_atomic_add_f32 v[158:159], v105, off offset:524
	global_atomic_add_f32 v[158:159], v98, off offset:576
	global_atomic_add_f32 v[158:159], v99, off offset:580
	global_atomic_add_f32 v[158:159], v100, off offset:584
	global_atomic_add_f32 v[158:159], v101, off offset:588
	global_atomic_add_f32 v[164:165], v92, off
	global_atomic_add_f32 v[162:163], v93, off offset:4
	global_atomic_add_f32 v[162:163], v94, off offset:8
	global_atomic_add_f32 v[162:163], v95, off offset:12
	global_atomic_add_f32 v[162:163], v88, off offset:64
	global_atomic_add_f32 v[162:163], v89, off offset:68
	global_atomic_add_f32 v[162:163], v90, off offset:72
	global_atomic_add_f32 v[162:163], v91, off offset:76
	global_atomic_add_f32 v[162:163], v84, off offset:512
	global_atomic_add_f32 v[162:163], v85, off offset:516
	global_atomic_add_f32 v[162:163], v86, off offset:520
	global_atomic_add_f32 v[162:163], v87, off offset:524
	global_atomic_add_f32 v[162:163], v80, off offset:576
	global_atomic_add_f32 v[162:163], v81, off offset:580
	global_atomic_add_f32 v[162:163], v82, off offset:584
;     DI void operator()(const f32x4 (&acc)[2][2][4][2], const Unit& u, int wr, int wc, int fr, int fq) const {
;     ...
;         for (int ai = 0; ai < 2; ++ai)
; #pragma unroll
;             for (int m = 0; m < 4; ++m) { float* rp = hp + (size_t)(wr * 64 + fr + ai * HALF + m * 16) * D + col0;
; #pragma unroll
;                 for (int bj = 0; bj < 2; ++bj)
; #pragma unroll
;                     for (int n = 0; n < 2; ++n) { const f32x4 v = gv[bj][n] * acc[ai][bj][m][n];
; #pragma unroll
;                         for (int j = 0; j < 4; ++j) __hip_atomic_fetch_add(rp + bj * HALF + n * 16 + j, v[j], __ATOMIC_RELAXED, __HIP_MEMORY_SCOPE_AGENT); } }
	global_atomic_add_f32 v[162:163], v83, off offset:588
	global_atomic_add_f32 v[170:171], v76, off
	v_mul_f32_e32 v76, v77, v143
	global_atomic_add_f32 v[168:169], v76, off offset:4
	v_mul_f32_e32 v76, v78, v144
	global_atomic_add_f32 v[168:169], v76, off offset:8
	v_mul_f32_e32 v76, v79, v145
	global_atomic_add_f32 v[168:169], v76, off offset:12
	v_mul_f32_e32 v72, v72, v138
	global_atomic_add_f32 v[168:169], v72, off offset:64
	v_mul_f32_e32 v72, v73, v139
	global_atomic_add_f32 v[168:169], v72, off offset:68
	v_mul_f32_e32 v72, v74, v140
	global_atomic_add_f32 v[168:169], v72, off offset:72
	v_mul_f32_e32 v72, v75, v141
	global_atomic_add_f32 v[168:169], v72, off offset:76
	v_mul_f32_e32 v68, v68, v134
	global_atomic_add_f32 v[168:169], v68, off offset:512
	v_mul_f32_e32 v68, v69, v135
	global_atomic_add_f32 v[168:169], v68, off offset:516
	v_mul_f32_e32 v68, v70, v136
	global_atomic_add_f32 v[168:169], v68, off offset:520
	v_mul_f32_e32 v68, v71, v137
	global_atomic_add_f32 v[168:169], v68, off offset:524
	v_mul_f32_e32 v64, v64, v130
	global_atomic_add_f32 v[168:169], v64, off offset:576
	v_mul_f32_e32 v64, v65, v131
	global_atomic_add_f32 v[168:169], v64, off offset:580
	v_mul_f32_e32 v64, v66, v132
	global_atomic_add_f32 v[168:169], v64, off offset:584
	v_mul_f32_e32 v64, v67, v133
	global_atomic_add_f32 v[168:169], v64, off offset:588
	v_lshl_add_u64 v[64:65], v[152:153], 0, s[6:7]
	s_mov_b32 s6, 0x100000
	v_add_co_u32_e32 v66, vcc, s6, v152
	v_mul_f32_e32 v60, v60, v142
	s_nop 0
	v_addc_co_u32_e32 v67, vcc, 0, v153, vcc
	global_atomic_add_f32 v[66:67], v60, off
	v_mul_f32_e32 v60, v61, v143
	global_atomic_add_f32 v[64:65], v60, off offset:4
	v_mul_f32_e32 v60, v62, v144
	global_atomic_add_f32 v[64:65], v60, off offset:8
	v_mul_f32_e32 v60, v63, v145
	global_atomic_add_f32 v[64:65], v60, off offset:12
	v_mul_f32_e32 v56, v56, v138
	global_atomic_add_f32 v[64:65], v56, off offset:64
	v_mul_f32_e32 v56, v57, v139
	global_atomic_add_f32 v[64:65], v56, off offset:68
	v_mul_f32_e32 v56, v58, v140
	global_atomic_add_f32 v[64:65], v56, off offset:72
	v_mul_f32_e32 v56, v59, v141
	global_atomic_add_f32 v[64:65], v56, off offset:76
	v_mul_f32_e32 v52, v52, v134
	global_atomic_add_f32 v[64:65], v52, off offset:512
	v_mul_f32_e32 v52, v53, v135
	global_atomic_add_f32 v[64:65], v52, off offset:516
	v_mul_f32_e32 v52, v54, v136
	global_atomic_add_f32 v[64:65], v52, off offset:520
	v_mul_f32_e32 v52, v55, v137
	global_atomic_add_f32 v[64:65], v52, off offset:524
	v_mul_f32_e32 v48, v48, v130
	global_atomic_add_f32 v[64:65], v48, off offset:576
	v_mul_f32_e32 v48, v49, v131
	global_atomic_add_f32 v[64:65], v48, off offset:580
	v_mul_f32_e32 v48, v50, v132
	global_atomic_add_f32 v[64:65], v48, off offset:584
	v_mul_f32_e32 v48, v51, v133
	s_mov_b64 s[6:7], 0x120000
	global_atomic_add_f32 v[64:65], v48, off offset:588
	v_lshl_add_u64 v[48:49], v[152:153], 0, s[6:7]
	s_mov_b32 s6, 0x120000
	v_add_co_u32_e32 v50, vcc, s6, v152
	v_mul_f32_e32 v44, v44, v142
	s_nop 0
	v_addc_co_u32_e32 v51, vcc, 0, v153, vcc
	global_atomic_add_f32 v[50:51], v44, off
	v_mul_f32_e32 v44, v45, v143
	global_atomic_add_f32 v[48:49], v44, off offset:4
	v_mul_f32_e32 v44, v46, v144
	global_atomic_add_f32 v[48:49], v44, off offset:8
	v_mul_f32_e32 v44, v47, v145
	global_atomic_add_f32 v[48:49], v44, off offset:12
	v_mul_f32_e32 v40, v40, v138
	global_atomic_add_f32 v[48:49], v40, off offset:64
	v_mul_f32_e32 v40, v41, v139
	global_atomic_add_f32 v[48:49], v40, off offset:68
	v_mul_f32_e32 v40, v42, v140
	global_atomic_add_f32 v[48:49], v40, off offset:72
	v_mul_f32_e32 v40, v43, v141
	global_atomic_add_f32 v[48:49], v40, off offset:76
;     DI void operator()(const f32x4 (&acc)[2][2][4][2], const Unit& u, int wr, int wc, int fr, int fq) const {
;     ...
;         for (int ai = 0; ai < 2; ++ai)
; #pragma unroll
;             for (int m = 0; m < 4; ++m) { float* rp = hp + (size_t)(wr * 64 + fr + ai * HALF + m * 16) * D + col0;
; #pragma unroll
;                 for (int bj = 0; bj < 2; ++bj)
; #pragma unroll
;                     for (int n = 0; n < 2; ++n) { const f32x4 v = gv[bj][n] * acc[ai][bj][m][n];
; #pragma unroll
;                         for (int j = 0; j < 4; ++j) __hip_atomic_fetch_add(rp + bj * HALF + n * 16 + j, v[j], __ATOMIC_RELAXED, __HIP_MEMORY_SCOPE_AGENT); } }
; template <class Epi, class Sched>
; DI void gemm_phase(LAS unsigned char* lds, const Gemm g, const Sched& S, const Epi& E) {
;     ...
;         { int fr_e = fr, fq_e = fq; asm volatile("" : "+v"(fr_e), "+v"(fq_e)); E(acc, cur, wr, wc, fr_e, fq_e); } S.done(cur);
;         __builtin_amdgcn_s_waitcnt(0x0F70);
;         if (!has_next) break;
	v_mul_f32_e32 v36, v36, v134
	global_atomic_add_f32 v[48:49], v36, off offset:512
	v_mul_f32_e32 v36, v37, v135
	global_atomic_add_f32 v[48:49], v36, off offset:516
	v_mul_f32_e32 v36, v38, v136
	global_atomic_add_f32 v[48:49], v36, off offset:520
	v_mul_f32_e32 v36, v39, v137
	global_atomic_add_f32 v[48:49], v36, off offset:524
	v_mul_f32_e32 v32, v32, v130
	global_atomic_add_f32 v[48:49], v32, off offset:576
	v_mul_f32_e32 v32, v33, v131
	global_atomic_add_f32 v[48:49], v32, off offset:580
	v_mul_f32_e32 v32, v34, v132
	global_atomic_add_f32 v[48:49], v32, off offset:584
	v_mul_f32_e32 v32, v35, v133
	s_mov_b64 s[6:7], 0x140000
	global_atomic_add_f32 v[48:49], v32, off offset:588
	v_lshl_add_u64 v[32:33], v[152:153], 0, s[6:7]
	s_mov_b32 s6, 0x140000
	v_add_co_u32_e32 v34, vcc, s6, v152
	v_mul_f32_e32 v28, v28, v142
	s_nop 0
	v_addc_co_u32_e32 v35, vcc, 0, v153, vcc
	global_atomic_add_f32 v[34:35], v28, off
	v_mul_f32_e32 v28, v29, v143
	global_atomic_add_f32 v[32:33], v28, off offset:4
	v_mul_f32_e32 v28, v30, v144
	global_atomic_add_f32 v[32:33], v28, off offset:8
	v_mul_f32_e32 v28, v31, v145
	global_atomic_add_f32 v[32:33], v28, off offset:12
	v_mul_f32_e32 v24, v24, v138
	global_atomic_add_f32 v[32:33], v24, off offset:64
	v_mul_f32_e32 v24, v25, v139
	global_atomic_add_f32 v[32:33], v24, off offset:68
	v_mul_f32_e32 v24, v26, v140
	global_atomic_add_f32 v[32:33], v24, off offset:72
	v_mul_f32_e32 v24, v27, v141
	global_atomic_add_f32 v[32:33], v24, off offset:76
	v_mul_f32_e32 v20, v20, v134
	global_atomic_add_f32 v[32:33], v20, off offset:512
	v_mul_f32_e32 v20, v21, v135
	global_atomic_add_f32 v[32:33], v20, off offset:516
	v_mul_f32_e32 v20, v22, v136
	global_atomic_add_f32 v[32:33], v20, off offset:520
	v_mul_f32_e32 v20, v23, v137
	global_atomic_add_f32 v[32:33], v20, off offset:524
	v_mul_f32_e32 v16, v16, v130
	global_atomic_add_f32 v[32:33], v16, off offset:576
	v_mul_f32_e32 v16, v17, v131
	global_atomic_add_f32 v[32:33], v16, off offset:580
	v_mul_f32_e32 v16, v18, v132
	global_atomic_add_f32 v[32:33], v16, off offset:584
	v_mul_f32_e32 v16, v19, v133
	s_mov_b64 s[6:7], 0x160000
	global_atomic_add_f32 v[32:33], v16, off offset:588
	v_lshl_add_u64 v[16:17], v[152:153], 0, s[6:7]
	s_mov_b32 s6, 0x160000
	v_add_co_u32_e32 v18, vcc, s6, v152
	v_mul_f32_e32 v12, v12, v142
	s_nop 0
	v_addc_co_u32_e32 v19, vcc, 0, v153, vcc
	global_atomic_add_f32 v[18:19], v12, off
	v_mul_f32_e32 v12, v13, v143
	global_atomic_add_f32 v[16:17], v12, off offset:4
	v_mul_f32_e32 v12, v14, v144
	global_atomic_add_f32 v[16:17], v12, off offset:8
	v_mul_f32_e32 v12, v15, v145
	global_atomic_add_f32 v[16:17], v12, off offset:12
	v_mul_f32_e32 v8, v8, v138
	global_atomic_add_f32 v[16:17], v8, off offset:64
	v_mul_f32_e32 v8, v9, v139
	global_atomic_add_f32 v[16:17], v8, off offset:68
	v_mul_f32_e32 v8, v10, v140
	global_atomic_add_f32 v[16:17], v8, off offset:72
	v_mul_f32_e32 v8, v11, v141
	global_atomic_add_f32 v[16:17], v8, off offset:76
	v_mul_f32_e32 v4, v4, v134
	global_atomic_add_f32 v[16:17], v4, off offset:512
	v_mul_f32_e32 v4, v5, v135
	global_atomic_add_f32 v[16:17], v4, off offset:516
	v_mul_f32_e32 v4, v6, v136
	global_atomic_add_f32 v[16:17], v4, off offset:520
	v_mul_f32_e32 v4, v7, v137
	global_atomic_add_f32 v[16:17], v4, off offset:524
	v_mul_f32_e32 v0, v0, v130
	global_atomic_add_f32 v[16:17], v0, off offset:576
	v_mul_f32_e32 v0, v1, v131
	global_atomic_add_f32 v[16:17], v0, off offset:580
	v_mul_f32_e32 v0, v2, v132
	global_atomic_add_f32 v[16:17], v0, off offset:584
	v_mul_f32_e32 v0, v3, v133
	global_atomic_add_f32 v[16:17], v0, off offset:588
	s_and_b64 vcc, exec, s[42:43]
	s_cbranch_vccnz .LBB0_55

;     DI void operator()(const f32x4 (&acc)[2][2][4][2], const Unit& u, int wr, int wc, int fr, int fq) const {
;         const int rbase = u.pm * BM + row_off; const bool isc = rbase < NCT; const int mr = isc ? 8 : ((rbase - NCT) >> 11);
;         const float* rp = isc ? res_c + (size_t)rbase * D : res_l + (size_t)(rbase - NCT) * D;
;         float* hp = isc ? h_c + (size_t)rbase * D : h_l + (size_t)(rbase - NCT) * D;
;         const float* g = gate + (size_t)mr * (6 * D);
;         const int col0 = u.pn * BM + wc * 32 + 4 * fq;
;         f32x4 gv[2][2];
; #pragma unroll
;         for (int bj = 0; bj < 2; ++bj)
; #pragma unroll
;             for (int n = 0; n < 2; ++n) gv[bj][n] = *(const f32x4*)(g + col0 + bj * HALF + n * 16);
; #pragma unroll
;         for (int ai = 0; ai < 2; ++ai) {
;             f32x4 r[4][2][2];
; #pragma unroll
;             for (int m = 0; m < 4; ++m) { const size_t ro = (size_t)(wr * 64 + fr + ai * HALF + m * 16) * D + col0;
; #pragma unroll
;                 for (int bj = 0; bj < 2; ++bj)
; #pragma unroll
;                     for (int n = 0; n < 2; ++n) r[m][bj][n] = *(const f32x4*)(rp + ro + bj * HALF + n * 16); }
;             __builtin_amdgcn_sched_barrier(0);
; #pragma unroll
;             for (int m = 0; m < 4; ++m) { const size_t ro = (size_t)(wr * 64 + fr + ai * HALF + m * 16) * D + col0;
; #pragma unroll
;                 for (int bj = 0; bj < 2; ++bj)
; #pragma unroll
;                     for (int n = 0; n < 2; ++n) *(f32x4*)(hp + ro + bj * HALF + n * 16) = r[m][bj][n] + gv[bj][n] * acc[ai][bj][m][n]; }
;             __builtin_amdgcn_sched_barrier(0);
;         }
.LBB0_66:
	s_add_u32 s8, s74, s8
	s_addc_u32 s9, s75, s9
	s_add_u32 s10, s94, s68
	s_addc_u32 s11, s95, s69
	s_lshl_b32 s30, s30, 8
	s_or_b32 s30, s30, s82
	v_lshl_add_u32 v130, v130, 2, s30
	v_ashrrev_i32_e32 v131, 31, v130
	v_add_u32_e32 v152, s97, v152
	v_lshlrev_b64 v[180:181], 2, v[130:131]
	v_ashrrev_i32_e32 v153, 31, v152
	v_lshl_add_u64 v[154:155], s[8:9], 0, v[180:181]
	v_lshlrev_b64 v[156:157], 13, v[152:153]
	s_mov_b64 s[2:3], 0x20000
	v_lshl_add_u64 v[130:131], s[10:11], 0, v[180:181]
	v_lshl_add_u64 v[152:153], v[154:155], 0, v[156:157]
	v_lshl_add_u64 v[244:245], v[156:157], 0, s[2:3]
	s_mov_b64 s[2:3], 0x40000
	global_load_dwordx4 v[142:145], v[130:131], off
	global_load_dwordx4 v[138:141], v[130:131], off offset:64
	global_load_dwordx4 v[134:137], v[130:131], off offset:512
	s_nop 0
	global_load_dwordx4 v[130:133], v[130:131], off offset:576
	s_nop 0
	global_load_dwordx4 v[162:165], v[152:153], off
	global_load_dwordx4 v[168:171], v[152:153], off offset:64
	global_load_dwordx4 v[172:175], v[152:153], off offset:512
	global_load_dwordx4 v[176:179], v[152:153], off offset:576
	v_lshl_add_u64 v[152:153], v[154:155], 0, v[244:245]
	v_lshl_add_u64 v[246:247], v[156:157], 0, s[2:3]
	s_mov_b64 s[2:3], 0x60000
	global_load_dwordx4 v[196:199], v[152:153], off
	global_load_dwordx4 v[200:203], v[152:153], off offset:64
	global_load_dwordx4 v[204:207], v[152:153], off offset:512
	global_load_dwordx4 v[208:211], v[152:153], off offset:576
	v_lshl_add_u64 v[152:153], v[154:155], 0, v[246:247]
	v_lshl_add_u64 v[248:249], v[156:157], 0, s[2:3]
	global_load_dwordx4 v[212:215], v[152:153], off
	global_load_dwordx4 v[216:219], v[152:153], off offset:64
	global_load_dwordx4 v[220:223], v[152:153], off offset:512
	global_load_dwordx4 v[224:227], v[152:153], off offset:576
	v_lshl_add_u64 v[152:153], v[154:155], 0, v[248:249]
	global_load_dwordx4 v[228:231], v[152:153], off
	global_load_dwordx4 v[232:235], v[152:153], off offset:64
	global_load_dwordx4 v[236:239], v[152:153], off offset:512
	global_load_dwordx4 v[240:243], v[152:153], off offset:576
	v_lshl_add_u64 v[152:153], s[6:7], 0, v[180:181]
	v_lshl_add_u64 v[180:181], v[152:153], 0, v[156:157]
	s_waitcnt vmcnt(0)
	v_pk_fma_f32 v[116:117], v[116:117], v[132:133], v[178:179]
	v_pk_fma_f32 v[114:115], v[114:115], v[130:131], v[176:177]
	global_store_dwordx4 v[180:181], v[114:117], off offset:576
	v_pk_fma_f32 v[100:101], v[100:101], v[132:133], v[210:211]
	v_pk_fma_f32 v[98:99], v[98:99], v[130:131], v[208:209]
	v_lshl_add_u64 v[114:115], v[152:153], 0, v[244:245]
	global_store_dwordx4 v[114:115], v[98:101], off offset:576
	v_pk_fma_f32 v[82:83], v[82:83], v[132:133], v[226:227]
	v_pk_fma_f32 v[80:81], v[80:81], v[130:131], v[224:225]
	v_lshl_add_u64 v[98:99], v[152:153], 0, v[246:247]
	v_pk_fma_f32 v[128:129], v[128:129], v[144:145], v[164:165]
	v_pk_fma_f32 v[126:127], v[126:127], v[142:143], v[162:163]
	v_pk_fma_f32 v[124:125], v[124:125], v[140:141], v[170:171]
	v_pk_fma_f32 v[122:123], v[122:123], v[138:139], v[168:169]
	v_pk_fma_f32 v[120:121], v[120:121], v[136:137], v[174:175]
	v_pk_fma_f32 v[118:119], v[118:119], v[134:135], v[172:173]
	v_pk_fma_f32 v[112:113], v[112:113], v[144:145], v[198:199]
	v_pk_fma_f32 v[110:111], v[110:111], v[142:143], v[196:197]
	v_pk_fma_f32 v[108:109], v[108:109], v[140:141], v[202:203]
	v_pk_fma_f32 v[106:107], v[106:107], v[138:139], v[200:201]
	v_pk_fma_f32 v[104:105], v[104:105], v[136:137], v[206:207]
	v_pk_fma_f32 v[102:103], v[102:103], v[134:135], v[204:205]
	v_pk_fma_f32 v[94:95], v[94:95], v[144:145], v[214:215]
	v_pk_fma_f32 v[92:93], v[92:93], v[142:143], v[212:213]
	v_pk_fma_f32 v[90:91], v[90:91], v[140:141], v[218:219]
	v_pk_fma_f32 v[88:89], v[88:89], v[138:139], v[216:217]
	v_pk_fma_f32 v[86:87], v[86:87], v[136:137], v[222:223]
	v_pk_fma_f32 v[84:85], v[84:85], v[134:135], v[220:221]
	global_store_dwordx4 v[98:99], v[80:83], off offset:576
	v_pk_fma_f32 v[78:79], v[78:79], v[144:145], v[230:231]
	v_pk_fma_f32 v[76:77], v[76:77], v[142:143], v[228:229]
	v_lshl_add_u64 v[80:81], v[152:153], 0, v[248:249]
	v_pk_fma_f32 v[74:75], v[74:75], v[140:141], v[234:235]
	v_pk_fma_f32 v[72:73], v[72:73], v[138:139], v[232:233]
	v_pk_fma_f32 v[70:71], v[70:71], v[136:137], v[238:239]
	v_pk_fma_f32 v[68:69], v[68:69], v[134:135], v[236:237]
	v_pk_fma_f32 v[66:67], v[66:67], v[132:133], v[242:243]
	v_pk_fma_f32 v[64:65], v[64:65], v[130:131], v[240:241]
	global_store_dwordx4 v[180:181], v[126:129], off
	global_store_dwordx4 v[180:181], v[122:125], off offset:64
	global_store_dwordx4 v[180:181], v[118:121], off offset:512
	global_store_dwordx4 v[114:115], v[110:113], off
	global_store_dwordx4 v[114:115], v[106:109], off offset:64
	global_store_dwordx4 v[114:115], v[102:105], off offset:512
	global_store_dwordx4 v[98:99], v[92:95], off
	global_store_dwordx4 v[98:99], v[88:91], off offset:64
	global_store_dwordx4 v[98:99], v[84:87], off offset:512
	global_store_dwordx4 v[80:81], v[76:79], off
	global_store_dwordx4 v[80:81], v[72:75], off offset:64
	global_store_dwordx4 v[80:81], v[68:71], off offset:512
	global_store_dwordx4 v[80:81], v[64:67], off offset:576
	s_mov_b64 s[2:3], 0x100000
	v_lshl_add_u64 v[162:163], v[156:157], 0, s[2:3]
	s_mov_b64 s[2:3], 0x120000
	v_lshl_add_u64 v[164:165], v[156:157], 0, s[2:3]
	s_mov_b64 s[2:3], 0x140000
	v_lshl_add_u64 v[168:169], v[156:157], 0, s[2:3]
	s_mov_b64 s[2:3], 0x160000
	v_lshl_add_u64 v[156:157], v[156:157], 0, s[2:3]
	v_lshl_add_u64 v[76:77], v[154:155], 0, v[162:163]
	v_lshl_add_u64 v[92:93], v[154:155], 0, v[164:165]
	v_lshl_add_u64 v[110:111], v[154:155], 0, v[168:169]
	v_lshl_add_u64 v[126:127], v[154:155], 0, v[156:157]
	global_load_dwordx4 v[64:67], v[76:77], off
	global_load_dwordx4 v[68:71], v[76:77], off offset:64
	global_load_dwordx4 v[72:75], v[76:77], off offset:512
	s_nop 0
	global_load_dwordx4 v[76:79], v[76:77], off offset:576
	s_nop 0
	global_load_dwordx4 v[80:83], v[92:93], off
	global_load_dwordx4 v[84:87], v[92:93], off offset:64
	global_load_dwordx4 v[88:91], v[92:93], off offset:512
	s_nop 0
	global_load_dwordx4 v[92:95], v[92:93], off offset:576
	s_nop 0
	global_load_dwordx4 v[98:101], v[110:111], off
	global_load_dwordx4 v[102:105], v[110:111], off offset:64
	global_load_dwordx4 v[106:109], v[110:111], off offset:512
	s_nop 0
	global_load_dwordx4 v[110:113], v[110:111], off offset:576
	s_nop 0
	global_load_dwordx4 v[114:117], v[126:127], off
	global_load_dwordx4 v[118:121], v[126:127], off offset:64
	global_load_dwordx4 v[122:125], v[126:127], off offset:512
	s_nop 0
	global_load_dwordx4 v[126:129], v[126:127], off offset:576
	v_lshl_add_u64 v[154:155], v[152:153], 0, v[162:163]
	s_waitcnt vmcnt(0)
;     DI void operator()(const f32x4 (&acc)[2][2][4][2], const Unit& u, int wr, int wc, int fr, int fq) const {
;     ...
;             for (int m = 0; m < 4; ++m) { const size_t ro = (size_t)(wr * 64 + fr + ai * HALF + m * 16) * D + col0;
; #pragma unroll
;                 for (int bj = 0; bj < 2; ++bj)
; #pragma unroll
;                     for (int n = 0; n < 2; ++n) *(f32x4*)(hp + ro + bj * HALF + n * 16) = r[m][bj][n] + gv[bj][n] * acc[ai][bj][m][n]; }
;             __builtin_amdgcn_sched_barrier(0);
;         }
; template <class Epi, class Sched>
; DI void gemm_phase(LAS unsigned char* lds, const Gemm g, const Sched& S, const Epi& E) {
;     ...
;         { int fr_e = fr, fq_e = fq; asm volatile("" : "+v"(fr_e), "+v"(fq_e)); E(acc, cur, wr, wc, fr_e, fq_e); } S.done(cur);
;         __builtin_amdgcn_s_waitcnt(0x0F70);
;         if (!has_next) break;
	v_pk_fma_f32 v[50:51], v[50:51], v[132:133], v[78:79]
	v_pk_fma_f32 v[48:49], v[48:49], v[130:131], v[76:77]
	global_store_dwordx4 v[154:155], v[48:51], off offset:576
	v_pk_fma_f32 v[34:35], v[34:35], v[132:133], v[94:95]
	v_pk_fma_f32 v[32:33], v[32:33], v[130:131], v[92:93]
	v_lshl_add_u64 v[48:49], v[152:153], 0, v[164:165]
	global_store_dwordx4 v[48:49], v[32:35], off offset:576
	v_pk_fma_f32 v[18:19], v[18:19], v[132:133], v[112:113]
	v_pk_fma_f32 v[16:17], v[16:17], v[130:131], v[110:111]
	v_lshl_add_u64 v[32:33], v[152:153], 0, v[168:169]
	v_pk_fma_f32 v[62:63], v[62:63], v[144:145], v[66:67]
	v_pk_fma_f32 v[60:61], v[60:61], v[142:143], v[64:65]
	v_pk_fma_f32 v[58:59], v[58:59], v[140:141], v[70:71]
	v_pk_fma_f32 v[56:57], v[56:57], v[138:139], v[68:69]
	v_pk_fma_f32 v[54:55], v[54:55], v[136:137], v[74:75]
	v_pk_fma_f32 v[52:53], v[52:53], v[134:135], v[72:73]
	v_pk_fma_f32 v[46:47], v[46:47], v[144:145], v[82:83]
	v_pk_fma_f32 v[44:45], v[44:45], v[142:143], v[80:81]
	v_pk_fma_f32 v[42:43], v[42:43], v[140:141], v[86:87]
	v_pk_fma_f32 v[40:41], v[40:41], v[138:139], v[84:85]
	v_pk_fma_f32 v[38:39], v[38:39], v[136:137], v[90:91]
	v_pk_fma_f32 v[36:37], v[36:37], v[134:135], v[88:89]
	v_pk_fma_f32 v[30:31], v[30:31], v[144:145], v[100:101]
	v_pk_fma_f32 v[28:29], v[28:29], v[142:143], v[98:99]
	v_pk_fma_f32 v[26:27], v[26:27], v[140:141], v[104:105]
	v_pk_fma_f32 v[24:25], v[24:25], v[138:139], v[102:103]
	v_pk_fma_f32 v[22:23], v[22:23], v[136:137], v[108:109]
	v_pk_fma_f32 v[20:21], v[20:21], v[134:135], v[106:107]
	global_store_dwordx4 v[32:33], v[16:19], off offset:576
	v_pk_fma_f32 v[14:15], v[14:15], v[144:145], v[116:117]
	v_pk_fma_f32 v[12:13], v[12:13], v[142:143], v[114:115]
	v_lshl_add_u64 v[16:17], v[152:153], 0, v[156:157]
	v_pk_fma_f32 v[10:11], v[10:11], v[140:141], v[120:121]
	v_pk_fma_f32 v[8:9], v[8:9], v[138:139], v[118:119]
	v_pk_fma_f32 v[6:7], v[6:7], v[136:137], v[124:125]
	v_pk_fma_f32 v[4:5], v[4:5], v[134:135], v[122:123]
	v_pk_fma_f32 v[2:3], v[2:3], v[132:133], v[128:129]
	v_pk_fma_f32 v[0:1], v[0:1], v[130:131], v[126:127]
	global_store_dwordx4 v[154:155], v[60:63], off
	global_store_dwordx4 v[154:155], v[56:59], off offset:64
	global_store_dwordx4 v[154:155], v[52:55], off offset:512
	global_store_dwordx4 v[48:49], v[44:47], off
	global_store_dwordx4 v[48:49], v[40:43], off offset:64
	global_store_dwordx4 v[48:49], v[36:39], off offset:512
	global_store_dwordx4 v[32:33], v[28:31], off
	global_store_dwordx4 v[32:33], v[24:27], off offset:64
	global_store_dwordx4 v[32:33], v[20:23], off offset:512
	global_store_dwordx4 v[16:17], v[12:15], off
	global_store_dwordx4 v[16:17], v[8:11], off offset:64
	global_store_dwordx4 v[16:17], v[4:7], off offset:512
	global_store_dwordx4 v[16:17], v[0:3], off offset:576
	s_and_b64 vcc, exec, s[42:43]
	s_mov_b32 s30, s41
	s_mov_b32 s10, s80
	s_mov_b64 s[68:69], s[46:47]
	s_mov_b64 s[56:57], s[44:45]
	s_cbranch_vccnz .LBB0_84

; DI unsigned cvt_pk_bf16(float lo, float hi) { return pack2(lo, hi); }
;     DI void operator()(const f32x4 (&acc)[2][2][4][2], const Unit& u, int wr, int wc, int fr, int fq) const {
;         const int row0 = u.pm * BM + row_off + wr * 64 + fr; const int col0 = u.pn * BM + wc * 32 + 8 * fq;
; #pragma unroll
;         for (int ai = 0; ai < 2; ++ai)
; #pragma unroll
;             for (int m = 0; m < 4; ++m) { bf16_t* rowp = O + (size_t)(row0 + ai * HALF + m * 16) * ldc + col0;
; #pragma unroll
;                 for (int bj = 0; bj < 2; ++bj) { f32x4 v0 = acc[ai][bj][m][0], v1 = acc[ai][bj][m][1];
;                     if (ACT == 3) {
; #pragma unroll
;                         for (int j = 0; j < 4; ++j) { float a = fmaxf(v0[j], 0.f), b = fmaxf(v1[j], 0.f); v0[j] = a * a; v1[j] = b * b; } }
;                     u32x4 w; w.x = cvt_pk_bf16(v0[0], v0[1]); w.y = cvt_pk_bf16(v0[2], v0[3]); w.z = cvt_pk_bf16(v1[0], v1[1]); w.w = cvt_pk_bf16(v1[2], v1[3]);
;                     *(u32x4*)(rowp + bj * HALF) = w; } }
.LBB0_97:
	s_lshl_b32 s7, s30, 8
	v_mov_b32_e32 v140, v144
	v_mov_b32_e32 v141, v145
	s_lshl_b32 s6, s31, 8
	s_or_b32 s7, s7, s94
	s_add_i32 s6, s61, s6
	v_lshl_add_u32 v142, v140, 3, s7
	v_max_f32_e32 v122, v122, v122
	v_max_f32_e32 v126, v126, v126
	v_max_f32_e32 v123, v123, v123
	v_max_f32_e32 v127, v127, v127
	v_max_f32_e32 v124, v124, v124
	v_max_f32_e32 v128, v128, v128
	v_max_f32_e32 v125, v125, v125
	v_max_f32_e32 v129, v129, v129
	v_add_u32_e32 v148, s6, v141
	v_ashrrev_i32_e32 v143, 31, v142
	v_mov_b64_e32 v[140:141], s[56:57]
	s_movk_i32 s3, 0x4080
	v_max_f32_e32 v122, 0, v122
	v_max_f32_e32 v126, 0, v126
	v_max_f32_e32 v123, 0, v123
	v_max_f32_e32 v127, 0, v127
	v_max_f32_e32 v124, 0, v124
	v_max_f32_e32 v128, 0, v128
	v_max_f32_e32 v125, 0, v125
	v_max_f32_e32 v129, 0, v129
	v_mad_i64_i32 v[150:151], s[6:7], v148, s3, v[140:141]
	v_lshlrev_b64 v[142:143], 1, v[142:143]
	v_pk_mul_f32 v[122:123], v[122:123], v[122:123]
	v_pk_mul_f32 v[126:127], v[126:127], v[126:127]
	v_pk_mul_f32 v[124:125], v[124:125], v[124:125]
	v_pk_mul_f32 v[128:129], v[128:129], v[128:129]
	v_max_f32_e32 v114, v114, v114
	v_max_f32_e32 v115, v115, v115
	v_lshl_add_u64 v[150:151], v[150:151], 0, v[142:143]
	v_cvt_pk_bf16_f32 v122, v122, v123
	v_cvt_pk_bf16_f32 v123, v124, v125
	v_cvt_pk_bf16_f32 v124, v126, v127
	v_cvt_pk_bf16_f32 v125, v128, v129
	v_max_f32_e32 v114, 0, v114
	v_max_f32_e32 v115, 0, v115
	global_store_dwordx4 v[150:151], v[122:125], off
	v_max_f32_e32 v118, v118, v118
	v_max_f32_e32 v119, v119, v119
	v_pk_mul_f32 v[122:123], v[114:115], v[114:115]
	v_max_f32_e32 v115, v116, v116
	v_max_f32_e32 v114, v120, v120
	v_max_f32_e32 v116, 0, v115
	v_max_f32_e32 v115, v121, v121
	v_max_f32_e32 v117, v117, v117
	v_max_f32_e32 v118, 0, v118
	v_max_f32_e32 v119, 0, v119
	v_max_f32_e32 v114, 0, v114
	v_max_f32_e32 v115, 0, v115
	v_max_f32_e32 v117, 0, v117
	v_pk_mul_f32 v[118:119], v[118:119], v[118:119]
	v_pk_mul_f32 v[120:121], v[114:115], v[114:115]
	v_pk_mul_f32 v[124:125], v[116:117], v[116:117]
	v_max_f32_e32 v106, v106, v106
	v_max_f32_e32 v107, v107, v107
	v_cvt_pk_bf16_f32 v114, v118, v119
	v_cvt_pk_bf16_f32 v115, v120, v121
	v_cvt_pk_bf16_f32 v116, v122, v123
	v_cvt_pk_bf16_f32 v117, v124, v125
	v_max_f32_e32 v106, 0, v106
	v_max_f32_e32 v107, 0, v107
	global_store_dwordx4 v[150:151], v[114:117], off offset:256
	v_max_f32_e32 v110, v110, v110
	v_max_f32_e32 v111, v111, v111
	v_pk_mul_f32 v[116:117], v[106:107], v[106:107]
	v_max_f32_e32 v107, v108, v108
	v_max_f32_e32 v106, v112, v112
	v_max_f32_e32 v108, 0, v107
	v_max_f32_e32 v107, v113, v113
	v_max_f32_e32 v109, v109, v109
	v_add_u32_e32 v114, 16, v148
	v_max_f32_e32 v110, 0, v110
	v_max_f32_e32 v111, 0, v111
	v_max_f32_e32 v106, 0, v106
	v_max_f32_e32 v107, 0, v107
	v_max_f32_e32 v109, 0, v109
	v_mad_i64_i32 v[114:115], s[6:7], v114, s3, v[140:141]
	v_pk_mul_f32 v[110:111], v[110:111], v[110:111]
	v_pk_mul_f32 v[112:113], v[106:107], v[106:107]
	v_pk_mul_f32 v[118:119], v[108:109], v[108:109]
	v_max_f32_e32 v98, v98, v98
	v_max_f32_e32 v99, v99, v99
	v_lshl_add_u64 v[114:115], v[114:115], 0, v[142:143]
	v_cvt_pk_bf16_f32 v106, v110, v111
	v_cvt_pk_bf16_f32 v107, v112, v113
	v_cvt_pk_bf16_f32 v108, v116, v117
	v_cvt_pk_bf16_f32 v109, v118, v119
	v_max_f32_e32 v98, 0, v98
	v_max_f32_e32 v99, 0, v99
	global_store_dwordx4 v[114:115], v[106:109], off
	v_max_f32_e32 v102, v102, v102
	v_max_f32_e32 v103, v103, v103
	v_pk_mul_f32 v[106:107], v[98:99], v[98:99]
	v_max_f32_e32 v99, v100, v100
	v_max_f32_e32 v98, v104, v104
	v_max_f32_e32 v100, 0, v99
	v_max_f32_e32 v99, v105, v105
	v_max_f32_e32 v101, v101, v101
	v_max_f32_e32 v102, 0, v102
	v_max_f32_e32 v103, 0, v103
	v_max_f32_e32 v98, 0, v98
	v_max_f32_e32 v99, 0, v99
	v_max_f32_e32 v101, 0, v101
	v_pk_mul_f32 v[102:103], v[102:103], v[102:103]
	v_pk_mul_f32 v[104:105], v[98:99], v[98:99]
	v_pk_mul_f32 v[108:109], v[100:101], v[100:101]
	v_max_f32_e32 v88, v88, v88
	v_max_f32_e32 v89, v89, v89
	v_cvt_pk_bf16_f32 v98, v102, v103
	v_cvt_pk_bf16_f32 v99, v104, v105
	v_cvt_pk_bf16_f32 v100, v106, v107
	v_cvt_pk_bf16_f32 v101, v108, v109
	v_max_f32_e32 v88, 0, v88
	v_max_f32_e32 v89, 0, v89
	global_store_dwordx4 v[114:115], v[98:101], off offset:256
	v_max_f32_e32 v92, v92, v92
	v_max_f32_e32 v93, v93, v93
	v_pk_mul_f32 v[100:101], v[88:89], v[88:89]
	v_max_f32_e32 v89, v90, v90
	v_max_f32_e32 v88, v94, v94
	v_max_f32_e32 v90, 0, v89
	v_max_f32_e32 v89, v95, v95
	v_max_f32_e32 v91, v91, v91
	v_add_u32_e32 v98, 32, v148
	v_max_f32_e32 v92, 0, v92
	v_max_f32_e32 v93, 0, v93
	v_max_f32_e32 v88, 0, v88
	v_max_f32_e32 v89, 0, v89
	v_max_f32_e32 v91, 0, v91
	v_mad_i64_i32 v[98:99], s[6:7], v98, s3, v[140:141]
	v_pk_mul_f32 v[92:93], v[92:93], v[92:93]
	v_pk_mul_f32 v[94:95], v[88:89], v[88:89]
	v_pk_mul_f32 v[102:103], v[90:91], v[90:91]
	v_max_f32_e32 v80, v80, v80
	v_max_f32_e32 v81, v81, v81
	v_lshl_add_u64 v[98:99], v[98:99], 0, v[142:143]
	v_cvt_pk_bf16_f32 v88, v92, v93
	v_cvt_pk_bf16_f32 v89, v94, v95
	v_cvt_pk_bf16_f32 v90, v100, v101
	v_cvt_pk_bf16_f32 v91, v102, v103
	v_max_f32_e32 v80, 0, v80
	v_max_f32_e32 v81, 0, v81
	global_store_dwordx4 v[98:99], v[88:91], off
	v_max_f32_e32 v84, v84, v84
	v_max_f32_e32 v85, v85, v85
	v_pk_mul_f32 v[88:89], v[80:81], v[80:81]
	v_max_f32_e32 v81, v82, v82
	v_max_f32_e32 v80, v86, v86
	v_max_f32_e32 v82, 0, v81
	v_max_f32_e32 v81, v87, v87
	v_max_f32_e32 v83, v83, v83
	v_max_f32_e32 v84, 0, v84
	v_max_f32_e32 v85, 0, v85
	v_max_f32_e32 v80, 0, v80
	v_max_f32_e32 v81, 0, v81
	v_max_f32_e32 v83, 0, v83
	v_pk_mul_f32 v[84:85], v[84:85], v[84:85]
	v_pk_mul_f32 v[86:87], v[80:81], v[80:81]
; DI unsigned cvt_pk_bf16(float lo, float hi) { return pack2(lo, hi); }
;     DI void operator()(const f32x4 (&acc)[2][2][4][2], const Unit& u, int wr, int wc, int fr, int fq) const {
;     ...
;         for (int ai = 0; ai < 2; ++ai)
; #pragma unroll
;             for (int m = 0; m < 4; ++m) { bf16_t* rowp = O + (size_t)(row0 + ai * HALF + m * 16) * ldc + col0;
; #pragma unroll
;                 for (int bj = 0; bj < 2; ++bj) { f32x4 v0 = acc[ai][bj][m][0], v1 = acc[ai][bj][m][1];
;                     if (ACT == 3) {
; #pragma unroll
;                         for (int j = 0; j < 4; ++j) { float a = fmaxf(v0[j], 0.f), b = fmaxf(v1[j], 0.f); v0[j] = a * a; v1[j] = b * b; } }
;                     u32x4 w; w.x = cvt_pk_bf16(v0[0], v0[1]); w.y = cvt_pk_bf16(v0[2], v0[3]); w.z = cvt_pk_bf16(v1[0], v1[1]); w.w = cvt_pk_bf16(v1[2], v1[3]);
;                     *(u32x4*)(rowp + bj * HALF) = w; } }
	v_pk_mul_f32 v[90:91], v[82:83], v[82:83]
	v_max_f32_e32 v72, v72, v72
	v_max_f32_e32 v73, v73, v73
	v_cvt_pk_bf16_f32 v80, v84, v85
	v_cvt_pk_bf16_f32 v81, v86, v87
	v_cvt_pk_bf16_f32 v82, v88, v89
	v_cvt_pk_bf16_f32 v83, v90, v91
	v_max_f32_e32 v72, 0, v72
	v_max_f32_e32 v73, 0, v73
	global_store_dwordx4 v[98:99], v[80:83], off offset:256
	v_max_f32_e32 v76, v76, v76
	v_max_f32_e32 v77, v77, v77
	v_pk_mul_f32 v[82:83], v[72:73], v[72:73]
	v_max_f32_e32 v73, v74, v74
	v_max_f32_e32 v72, v78, v78
	v_max_f32_e32 v74, 0, v73
	v_max_f32_e32 v73, v79, v79
	v_max_f32_e32 v75, v75, v75
	v_add_u32_e32 v80, 48, v148
	v_max_f32_e32 v76, 0, v76
	v_max_f32_e32 v77, 0, v77
	v_max_f32_e32 v72, 0, v72
	v_max_f32_e32 v73, 0, v73
	v_max_f32_e32 v75, 0, v75
	v_mad_i64_i32 v[80:81], s[6:7], v80, s3, v[140:141]
	v_pk_mul_f32 v[76:77], v[76:77], v[76:77]
	v_pk_mul_f32 v[78:79], v[72:73], v[72:73]
	v_pk_mul_f32 v[84:85], v[74:75], v[74:75]
	v_max_f32_e32 v64, v64, v64
	v_max_f32_e32 v65, v65, v65
	v_lshl_add_u64 v[80:81], v[80:81], 0, v[142:143]
	v_cvt_pk_bf16_f32 v72, v76, v77
	v_cvt_pk_bf16_f32 v73, v78, v79
	v_cvt_pk_bf16_f32 v74, v82, v83
	v_cvt_pk_bf16_f32 v75, v84, v85
	v_max_f32_e32 v64, 0, v64
	v_max_f32_e32 v65, 0, v65
	global_store_dwordx4 v[80:81], v[72:75], off
	v_max_f32_e32 v68, v68, v68
	v_max_f32_e32 v69, v69, v69
	v_pk_mul_f32 v[72:73], v[64:65], v[64:65]
	v_max_f32_e32 v65, v66, v66
	v_max_f32_e32 v64, v70, v70
	v_max_f32_e32 v66, 0, v65
	v_max_f32_e32 v65, v71, v71
	v_max_f32_e32 v67, v67, v67
	v_max_f32_e32 v68, 0, v68
	v_max_f32_e32 v69, 0, v69
	v_max_f32_e32 v64, 0, v64
	v_max_f32_e32 v65, 0, v65
	v_max_f32_e32 v67, 0, v67
	v_pk_mul_f32 v[68:69], v[68:69], v[68:69]
	v_pk_mul_f32 v[70:71], v[64:65], v[64:65]
	v_pk_mul_f32 v[74:75], v[66:67], v[66:67]
	v_max_f32_e32 v56, v56, v56
	v_max_f32_e32 v57, v57, v57
	v_cvt_pk_bf16_f32 v64, v68, v69
	v_cvt_pk_bf16_f32 v65, v70, v71
	v_cvt_pk_bf16_f32 v66, v72, v73
	v_cvt_pk_bf16_f32 v67, v74, v75
	v_max_f32_e32 v56, 0, v56
	v_max_f32_e32 v57, 0, v57
	global_store_dwordx4 v[80:81], v[64:67], off offset:256
	v_max_f32_e32 v60, v60, v60
	v_max_f32_e32 v61, v61, v61
	v_pk_mul_f32 v[66:67], v[56:57], v[56:57]
	v_max_f32_e32 v57, v58, v58
	v_max_f32_e32 v56, v62, v62
	v_max_f32_e32 v58, 0, v57
	v_max_f32_e32 v57, v63, v63
	v_max_f32_e32 v59, v59, v59
	v_add_u32_e32 v64, 0x80, v148
	v_max_f32_e32 v60, 0, v60
	v_max_f32_e32 v61, 0, v61
	v_max_f32_e32 v56, 0, v56
	v_max_f32_e32 v57, 0, v57
	v_max_f32_e32 v59, 0, v59
	v_mad_i64_i32 v[64:65], s[6:7], v64, s3, v[140:141]
	v_pk_mul_f32 v[60:61], v[60:61], v[60:61]
	v_pk_mul_f32 v[62:63], v[56:57], v[56:57]
	v_pk_mul_f32 v[68:69], v[58:59], v[58:59]
	v_max_f32_e32 v48, v48, v48
	v_max_f32_e32 v49, v49, v49
	v_lshl_add_u64 v[64:65], v[64:65], 0, v[142:143]
	v_cvt_pk_bf16_f32 v56, v60, v61
	v_cvt_pk_bf16_f32 v57, v62, v63
	v_cvt_pk_bf16_f32 v58, v66, v67
	v_cvt_pk_bf16_f32 v59, v68, v69
	v_max_f32_e32 v48, 0, v48
	v_max_f32_e32 v49, 0, v49
	global_store_dwordx4 v[64:65], v[56:59], off
	v_max_f32_e32 v52, v52, v52
	v_max_f32_e32 v53, v53, v53
	v_pk_mul_f32 v[56:57], v[48:49], v[48:49]
	v_max_f32_e32 v49, v50, v50
	v_max_f32_e32 v48, v54, v54
	v_max_f32_e32 v50, 0, v49
	v_max_f32_e32 v49, v55, v55
	v_max_f32_e32 v51, v51, v51
	v_max_f32_e32 v52, 0, v52
	v_max_f32_e32 v53, 0, v53
	v_max_f32_e32 v48, 0, v48
	v_max_f32_e32 v49, 0, v49
	v_max_f32_e32 v51, 0, v51
	v_pk_mul_f32 v[52:53], v[52:53], v[52:53]
	v_pk_mul_f32 v[54:55], v[48:49], v[48:49]
	v_pk_mul_f32 v[58:59], v[50:51], v[50:51]
	v_max_f32_e32 v40, v40, v40
	v_max_f32_e32 v41, v41, v41
	v_cvt_pk_bf16_f32 v48, v52, v53
	v_cvt_pk_bf16_f32 v49, v54, v55
	v_cvt_pk_bf16_f32 v50, v56, v57
	v_cvt_pk_bf16_f32 v51, v58, v59
	v_max_f32_e32 v40, 0, v40
	v_max_f32_e32 v41, 0, v41
	global_store_dwordx4 v[64:65], v[48:51], off offset:256
	v_max_f32_e32 v44, v44, v44
	v_max_f32_e32 v45, v45, v45
	v_pk_mul_f32 v[50:51], v[40:41], v[40:41]
	v_max_f32_e32 v41, v42, v42
	v_max_f32_e32 v40, v46, v46
	v_max_f32_e32 v42, 0, v41
	v_max_f32_e32 v41, v47, v47
	v_max_f32_e32 v43, v43, v43
	v_add_u32_e32 v48, 0x90, v148
	v_max_f32_e32 v44, 0, v44
	v_max_f32_e32 v45, 0, v45
	v_max_f32_e32 v40, 0, v40
	v_max_f32_e32 v41, 0, v41
	v_max_f32_e32 v43, 0, v43
	v_mad_i64_i32 v[48:49], s[6:7], v48, s3, v[140:141]
	v_pk_mul_f32 v[44:45], v[44:45], v[44:45]
	v_pk_mul_f32 v[46:47], v[40:41], v[40:41]
	v_pk_mul_f32 v[52:53], v[42:43], v[42:43]
	v_max_f32_e32 v32, v32, v32
	v_max_f32_e32 v33, v33, v33
; DI unsigned cvt_pk_bf16(float lo, float hi) { return pack2(lo, hi); }
;     DI void operator()(const f32x4 (&acc)[2][2][4][2], const Unit& u, int wr, int wc, int fr, int fq) const {
;     ...
;         for (int ai = 0; ai < 2; ++ai)
; #pragma unroll
;             for (int m = 0; m < 4; ++m) { bf16_t* rowp = O + (size_t)(row0 + ai * HALF + m * 16) * ldc + col0;
; #pragma unroll
;                 for (int bj = 0; bj < 2; ++bj) { f32x4 v0 = acc[ai][bj][m][0], v1 = acc[ai][bj][m][1];
;                     if (ACT == 3) {
; #pragma unroll
;                         for (int j = 0; j < 4; ++j) { float a = fmaxf(v0[j], 0.f), b = fmaxf(v1[j], 0.f); v0[j] = a * a; v1[j] = b * b; } }
;                     u32x4 w; w.x = cvt_pk_bf16(v0[0], v0[1]); w.y = cvt_pk_bf16(v0[2], v0[3]); w.z = cvt_pk_bf16(v1[0], v1[1]); w.w = cvt_pk_bf16(v1[2], v1[3]);
;                     *(u32x4*)(rowp + bj * HALF) = w; } }
; template <class Epi, class Sched>
; DI void gemm_phase(LAS unsigned char* lds, const Gemm g, const Sched& S, const Epi& E) {
;     ...
;         { int fr_e = fr, fq_e = fq; asm volatile("" : "+v"(fr_e), "+v"(fq_e)); E(acc, cur, wr, wc, fr_e, fq_e); } S.done(cur);
;         __builtin_amdgcn_s_waitcnt(0x0F70);
;         if (!has_next) break;
	v_lshl_add_u64 v[48:49], v[48:49], 0, v[142:143]
	v_cvt_pk_bf16_f32 v40, v44, v45
	v_cvt_pk_bf16_f32 v41, v46, v47
	v_cvt_pk_bf16_f32 v42, v50, v51
	v_cvt_pk_bf16_f32 v43, v52, v53
	v_max_f32_e32 v32, 0, v32
	v_max_f32_e32 v33, 0, v33
	global_store_dwordx4 v[48:49], v[40:43], off
	v_max_f32_e32 v36, v36, v36
	v_max_f32_e32 v37, v37, v37
	v_pk_mul_f32 v[40:41], v[32:33], v[32:33]
	v_max_f32_e32 v33, v34, v34
	v_max_f32_e32 v32, v38, v38
	v_max_f32_e32 v34, 0, v33
	v_max_f32_e32 v33, v39, v39
	v_max_f32_e32 v35, v35, v35
	v_max_f32_e32 v36, 0, v36
	v_max_f32_e32 v37, 0, v37
	v_max_f32_e32 v32, 0, v32
	v_max_f32_e32 v33, 0, v33
	v_max_f32_e32 v35, 0, v35
	v_pk_mul_f32 v[36:37], v[36:37], v[36:37]
	v_pk_mul_f32 v[38:39], v[32:33], v[32:33]
	v_pk_mul_f32 v[42:43], v[34:35], v[34:35]
	v_max_f32_e32 v24, v24, v24
	v_max_f32_e32 v25, v25, v25
	v_cvt_pk_bf16_f32 v32, v36, v37
	v_cvt_pk_bf16_f32 v33, v38, v39
	v_cvt_pk_bf16_f32 v34, v40, v41
	v_cvt_pk_bf16_f32 v35, v42, v43
	v_max_f32_e32 v24, 0, v24
	v_max_f32_e32 v25, 0, v25
	global_store_dwordx4 v[48:49], v[32:35], off offset:256
	v_max_f32_e32 v28, v28, v28
	v_max_f32_e32 v29, v29, v29
	v_pk_mul_f32 v[34:35], v[24:25], v[24:25]
	v_max_f32_e32 v25, v26, v26
	v_max_f32_e32 v24, v30, v30
	v_max_f32_e32 v26, 0, v25
	v_max_f32_e32 v25, v31, v31
	v_max_f32_e32 v27, v27, v27
	v_add_u32_e32 v32, 0xa0, v148
	v_max_f32_e32 v28, 0, v28
	v_max_f32_e32 v29, 0, v29
	v_max_f32_e32 v24, 0, v24
	v_max_f32_e32 v25, 0, v25
	v_max_f32_e32 v27, 0, v27
	v_mad_i64_i32 v[32:33], s[6:7], v32, s3, v[140:141]
	v_pk_mul_f32 v[28:29], v[28:29], v[28:29]
	v_pk_mul_f32 v[30:31], v[24:25], v[24:25]
	v_pk_mul_f32 v[36:37], v[26:27], v[26:27]
	v_max_f32_e32 v16, v16, v16
	v_max_f32_e32 v17, v17, v17
	v_lshl_add_u64 v[32:33], v[32:33], 0, v[142:143]
	v_cvt_pk_bf16_f32 v24, v28, v29
	v_cvt_pk_bf16_f32 v25, v30, v31
	v_cvt_pk_bf16_f32 v26, v34, v35
	v_cvt_pk_bf16_f32 v27, v36, v37
	v_max_f32_e32 v16, 0, v16
	v_max_f32_e32 v17, 0, v17
	global_store_dwordx4 v[32:33], v[24:27], off
	v_max_f32_e32 v20, v20, v20
	v_max_f32_e32 v21, v21, v21
	v_pk_mul_f32 v[24:25], v[16:17], v[16:17]
	v_max_f32_e32 v17, v18, v18
	v_max_f32_e32 v16, v22, v22
	v_max_f32_e32 v18, 0, v17
	v_max_f32_e32 v17, v23, v23
	v_max_f32_e32 v19, v19, v19
	v_max_f32_e32 v20, 0, v20
	v_max_f32_e32 v21, 0, v21
	v_max_f32_e32 v16, 0, v16
	v_max_f32_e32 v17, 0, v17
	v_max_f32_e32 v19, 0, v19
	v_pk_mul_f32 v[20:21], v[20:21], v[20:21]
	v_pk_mul_f32 v[22:23], v[16:17], v[16:17]
	v_pk_mul_f32 v[26:27], v[18:19], v[18:19]
	v_max_f32_e32 v8, v8, v8
	v_max_f32_e32 v9, v9, v9
	v_cvt_pk_bf16_f32 v16, v20, v21
	v_cvt_pk_bf16_f32 v17, v22, v23
	v_cvt_pk_bf16_f32 v18, v24, v25
	v_cvt_pk_bf16_f32 v19, v26, v27
	v_max_f32_e32 v8, 0, v8
	v_max_f32_e32 v9, 0, v9
	global_store_dwordx4 v[32:33], v[16:19], off offset:256
	v_max_f32_e32 v12, v12, v12
	v_max_f32_e32 v13, v13, v13
	v_pk_mul_f32 v[18:19], v[8:9], v[8:9]
	v_max_f32_e32 v9, v10, v10
	v_max_f32_e32 v8, v14, v14
	v_max_f32_e32 v10, 0, v9
	v_max_f32_e32 v9, v15, v15
	v_max_f32_e32 v11, v11, v11
	v_add_u32_e32 v16, 0xb0, v148
	v_max_f32_e32 v12, 0, v12
	v_max_f32_e32 v13, 0, v13
	v_max_f32_e32 v8, 0, v8
	v_max_f32_e32 v9, 0, v9
	v_max_f32_e32 v11, 0, v11
	v_mad_i64_i32 v[16:17], s[6:7], v16, s3, v[140:141]
	v_pk_mul_f32 v[12:13], v[12:13], v[12:13]
	v_pk_mul_f32 v[14:15], v[8:9], v[8:9]
	v_pk_mul_f32 v[20:21], v[10:11], v[10:11]
	v_max_f32_e32 v0, v0, v0
	v_max_f32_e32 v1, v1, v1
	v_lshl_add_u64 v[16:17], v[16:17], 0, v[142:143]
	v_cvt_pk_bf16_f32 v8, v12, v13
	v_cvt_pk_bf16_f32 v9, v14, v15
	v_cvt_pk_bf16_f32 v10, v18, v19
	v_cvt_pk_bf16_f32 v11, v20, v21
	v_max_f32_e32 v0, 0, v0
	v_max_f32_e32 v1, 0, v1
	global_store_dwordx4 v[16:17], v[8:11], off
	v_max_f32_e32 v4, v4, v4
	v_max_f32_e32 v5, v5, v5
	v_pk_mul_f32 v[8:9], v[0:1], v[0:1]
	v_max_f32_e32 v1, v2, v2
	v_max_f32_e32 v0, v6, v6
	v_max_f32_e32 v2, 0, v1
	v_max_f32_e32 v1, v7, v7
	v_max_f32_e32 v3, v3, v3
	v_max_f32_e32 v4, 0, v4
	v_max_f32_e32 v5, 0, v5
	v_max_f32_e32 v0, 0, v0
	v_max_f32_e32 v1, 0, v1
	v_max_f32_e32 v3, 0, v3
	v_pk_mul_f32 v[4:5], v[4:5], v[4:5]
	v_pk_mul_f32 v[6:7], v[0:1], v[0:1]
	v_pk_mul_f32 v[10:11], v[2:3], v[2:3]
	v_cvt_pk_bf16_f32 v0, v4, v5
	v_cvt_pk_bf16_f32 v1, v6, v7
	v_cvt_pk_bf16_f32 v2, v8, v9
	v_cvt_pk_bf16_f32 v3, v10, v11
	s_and_b64 vcc, exec, s[42:43]
	s_mov_b32 s30, s24
	s_mov_b32 s31, s27
	s_mov_b64 s[74:75], s[46:47]
	s_mov_b64 s[82:83], s[44:45]
	global_store_dwordx4 v[16:17], v[0:3], off offset:256
	s_cbranch_vccnz .LBB0_111

;     DI void operator()(const f32x4 (&acc)[2][2][4][2], const Unit& u, int wr, int wc, int fr, int fq) const {
;         const int rbase = u.pm * BM + row_off; const bool isc = rbase < NCT; const int mr = isc ? 8 : ((rbase - NCT) >> 11);
;         const float* rp = isc ? res_c + (size_t)rbase * D : res_l + (size_t)(rbase - NCT) * D;
;         float* hp = isc ? h_c + (size_t)rbase * D : h_l + (size_t)(rbase - NCT) * D;
;         const float* g = gate + (size_t)mr * (6 * D);
;         const int col0 = u.pn * BM + wc * 32 + 4 * fq;
;         f32x4 gv[2][2];
; #pragma unroll
;         for (int bj = 0; bj < 2; ++bj)
; #pragma unroll
;             for (int n = 0; n < 2; ++n) gv[bj][n] = *(const f32x4*)(g + col0 + bj * HALF + n * 16);
; #pragma unroll
;         for (int ai = 0; ai < 2; ++ai) {
;             f32x4 r[4][2][2];
; #pragma unroll
;             for (int m = 0; m < 4; ++m) { const size_t ro = (size_t)(wr * 64 + fr + ai * HALF + m * 16) * D + col0;
; #pragma unroll
;                 for (int bj = 0; bj < 2; ++bj)
; #pragma unroll
;                     for (int n = 0; n < 2; ++n) r[m][bj][n] = *(const f32x4*)(rp + ro + bj * HALF + n * 16); }
;             __builtin_amdgcn_sched_barrier(0);
; #pragma unroll
;             for (int m = 0; m < 4; ++m) { const size_t ro = (size_t)(wr * 64 + fr + ai * HALF + m * 16) * D + col0;
; #pragma unroll
;                 for (int bj = 0; bj < 2; ++bj)
; #pragma unroll
;                     for (int n = 0; n < 2; ++n) *(f32x4*)(hp + ro + bj * HALF + n * 16) = r[m][bj][n] + gv[bj][n] * acc[ai][bj][m][n]; }
.LBB0_172:
	s_add_u32 s8, s82, s74
	s_addc_u32 s9, s83, s75
	s_add_u32 s10, s97, s76
	s_addc_u32 s11, s84, s77
	s_lshl_b32 s31, s80, 8
	s_or_b32 s31, s31, s78
	v_lshl_add_u32 v130, v130, 2, s31
	v_ashrrev_i32_e32 v131, 31, v130
	v_add_u32_e32 v152, s73, v152
	v_lshlrev_b64 v[180:181], 2, v[130:131]
	v_ashrrev_i32_e32 v153, 31, v152
	v_lshl_add_u64 v[154:155], s[8:9], 0, v[180:181]
	v_lshlrev_b64 v[156:157], 13, v[152:153]
	s_mov_b64 s[8:9], 0x20000
	v_lshl_add_u64 v[130:131], s[10:11], 0, v[180:181]
	v_lshl_add_u64 v[152:153], v[154:155], 0, v[156:157]
	v_lshl_add_u64 v[244:245], v[156:157], 0, s[8:9]
	s_mov_b64 s[8:9], 0x40000
	global_load_dwordx4 v[142:145], v[130:131], off
	global_load_dwordx4 v[138:141], v[130:131], off offset:64
	global_load_dwordx4 v[134:137], v[130:131], off offset:512
	s_nop 0
	global_load_dwordx4 v[130:133], v[130:131], off offset:576
	s_nop 0
	global_load_dwordx4 v[162:165], v[152:153], off
	global_load_dwordx4 v[168:171], v[152:153], off offset:64
	global_load_dwordx4 v[172:175], v[152:153], off offset:512
	global_load_dwordx4 v[176:179], v[152:153], off offset:576
	v_lshl_add_u64 v[152:153], v[154:155], 0, v[244:245]
	v_lshl_add_u64 v[246:247], v[156:157], 0, s[8:9]
	s_mov_b64 s[8:9], 0x60000
	global_load_dwordx4 v[196:199], v[152:153], off
	global_load_dwordx4 v[200:203], v[152:153], off offset:64
	global_load_dwordx4 v[204:207], v[152:153], off offset:512
	global_load_dwordx4 v[208:211], v[152:153], off offset:576
	v_lshl_add_u64 v[152:153], v[154:155], 0, v[246:247]
	v_lshl_add_u64 v[248:249], v[156:157], 0, s[8:9]
	global_load_dwordx4 v[212:215], v[152:153], off
	global_load_dwordx4 v[216:219], v[152:153], off offset:64
	global_load_dwordx4 v[220:223], v[152:153], off offset:512
	global_load_dwordx4 v[224:227], v[152:153], off offset:576
	v_lshl_add_u64 v[152:153], v[154:155], 0, v[248:249]
	global_load_dwordx4 v[228:231], v[152:153], off
	global_load_dwordx4 v[232:235], v[152:153], off offset:64
	global_load_dwordx4 v[236:239], v[152:153], off offset:512
	global_load_dwordx4 v[240:243], v[152:153], off offset:576
	v_lshl_add_u64 v[152:153], s[6:7], 0, v[180:181]
	v_lshl_add_u64 v[180:181], v[152:153], 0, v[156:157]
	s_waitcnt vmcnt(0)
	v_pk_fma_f32 v[116:117], v[116:117], v[132:133], v[178:179]
	v_pk_fma_f32 v[114:115], v[114:115], v[130:131], v[176:177]
	global_store_dwordx4 v[180:181], v[114:117], off offset:576
	v_pk_fma_f32 v[100:101], v[100:101], v[132:133], v[210:211]
	v_pk_fma_f32 v[98:99], v[98:99], v[130:131], v[208:209]
	v_lshl_add_u64 v[114:115], v[152:153], 0, v[244:245]
	global_store_dwordx4 v[114:115], v[98:101], off offset:576
	v_pk_fma_f32 v[82:83], v[82:83], v[132:133], v[226:227]
	v_pk_fma_f32 v[80:81], v[80:81], v[130:131], v[224:225]
	v_lshl_add_u64 v[98:99], v[152:153], 0, v[246:247]
	v_pk_fma_f32 v[128:129], v[128:129], v[144:145], v[164:165]
	v_pk_fma_f32 v[126:127], v[126:127], v[142:143], v[162:163]
	v_pk_fma_f32 v[124:125], v[124:125], v[140:141], v[170:171]
	v_pk_fma_f32 v[122:123], v[122:123], v[138:139], v[168:169]
	v_pk_fma_f32 v[120:121], v[120:121], v[136:137], v[174:175]
	v_pk_fma_f32 v[118:119], v[118:119], v[134:135], v[172:173]
	v_pk_fma_f32 v[112:113], v[112:113], v[144:145], v[198:199]
	v_pk_fma_f32 v[110:111], v[110:111], v[142:143], v[196:197]
	v_pk_fma_f32 v[108:109], v[108:109], v[140:141], v[202:203]
	v_pk_fma_f32 v[106:107], v[106:107], v[138:139], v[200:201]
	v_pk_fma_f32 v[104:105], v[104:105], v[136:137], v[206:207]
	v_pk_fma_f32 v[102:103], v[102:103], v[134:135], v[204:205]
	v_pk_fma_f32 v[94:95], v[94:95], v[144:145], v[214:215]
	v_pk_fma_f32 v[92:93], v[92:93], v[142:143], v[212:213]
	v_pk_fma_f32 v[90:91], v[90:91], v[140:141], v[218:219]
	v_pk_fma_f32 v[88:89], v[88:89], v[138:139], v[216:217]
	v_pk_fma_f32 v[86:87], v[86:87], v[136:137], v[222:223]
	v_pk_fma_f32 v[84:85], v[84:85], v[134:135], v[220:221]
	global_store_dwordx4 v[98:99], v[80:83], off offset:576
	v_pk_fma_f32 v[78:79], v[78:79], v[144:145], v[230:231]
	v_pk_fma_f32 v[76:77], v[76:77], v[142:143], v[228:229]
	v_lshl_add_u64 v[80:81], v[152:153], 0, v[248:249]
	v_pk_fma_f32 v[74:75], v[74:75], v[140:141], v[234:235]
	v_pk_fma_f32 v[72:73], v[72:73], v[138:139], v[232:233]
	v_pk_fma_f32 v[70:71], v[70:71], v[136:137], v[238:239]
	v_pk_fma_f32 v[68:69], v[68:69], v[134:135], v[236:237]
	v_pk_fma_f32 v[66:67], v[66:67], v[132:133], v[242:243]
	v_pk_fma_f32 v[64:65], v[64:65], v[130:131], v[240:241]
	global_store_dwordx4 v[180:181], v[126:129], off
	global_store_dwordx4 v[180:181], v[122:125], off offset:64
	global_store_dwordx4 v[180:181], v[118:121], off offset:512
	global_store_dwordx4 v[114:115], v[110:113], off
	global_store_dwordx4 v[114:115], v[106:109], off offset:64
	global_store_dwordx4 v[114:115], v[102:105], off offset:512
	global_store_dwordx4 v[98:99], v[92:95], off
	global_store_dwordx4 v[98:99], v[88:91], off offset:64
	global_store_dwordx4 v[98:99], v[84:87], off offset:512
	global_store_dwordx4 v[80:81], v[76:79], off
	global_store_dwordx4 v[80:81], v[72:75], off offset:64
	global_store_dwordx4 v[80:81], v[68:71], off offset:512
	global_store_dwordx4 v[80:81], v[64:67], off offset:576
	s_mov_b64 s[6:7], 0x100000
	v_lshl_add_u64 v[162:163], v[156:157], 0, s[6:7]
	s_mov_b64 s[6:7], 0x120000
	v_lshl_add_u64 v[164:165], v[156:157], 0, s[6:7]
	s_mov_b64 s[6:7], 0x140000
	v_lshl_add_u64 v[168:169], v[156:157], 0, s[6:7]
	s_mov_b64 s[6:7], 0x160000
	v_lshl_add_u64 v[156:157], v[156:157], 0, s[6:7]
	v_lshl_add_u64 v[76:77], v[154:155], 0, v[162:163]
	v_lshl_add_u64 v[92:93], v[154:155], 0, v[164:165]
	v_lshl_add_u64 v[110:111], v[154:155], 0, v[168:169]
	v_lshl_add_u64 v[126:127], v[154:155], 0, v[156:157]
	global_load_dwordx4 v[64:67], v[76:77], off
	global_load_dwordx4 v[68:71], v[76:77], off offset:64
	global_load_dwordx4 v[72:75], v[76:77], off offset:512
	s_nop 0
	global_load_dwordx4 v[76:79], v[76:77], off offset:576
	s_nop 0
	global_load_dwordx4 v[80:83], v[92:93], off
	global_load_dwordx4 v[84:87], v[92:93], off offset:64
	global_load_dwordx4 v[88:91], v[92:93], off offset:512
	s_nop 0
	global_load_dwordx4 v[92:95], v[92:93], off offset:576
	s_nop 0
	global_load_dwordx4 v[98:101], v[110:111], off
	global_load_dwordx4 v[102:105], v[110:111], off offset:64
	global_load_dwordx4 v[106:109], v[110:111], off offset:512
	s_nop 0
	global_load_dwordx4 v[110:113], v[110:111], off offset:576
	s_nop 0
	global_load_dwordx4 v[114:117], v[126:127], off
	global_load_dwordx4 v[118:121], v[126:127], off offset:64
	global_load_dwordx4 v[122:125], v[126:127], off offset:512
	s_nop 0
	global_load_dwordx4 v[126:129], v[126:127], off offset:576
	v_lshl_add_u64 v[154:155], v[152:153], 0, v[162:163]
	s_waitcnt vmcnt(0)
;     DI void operator()(const f32x4 (&acc)[2][2][4][2], const Unit& u, int wr, int wc, int fr, int fq) const {
;     ...
;             for (int m = 0; m < 4; ++m) { const size_t ro = (size_t)(wr * 64 + fr + ai * HALF + m * 16) * D + col0;
; #pragma unroll
;                 for (int bj = 0; bj < 2; ++bj)
; #pragma unroll
;                     for (int n = 0; n < 2; ++n) *(f32x4*)(hp + ro + bj * HALF + n * 16) = r[m][bj][n] + gv[bj][n] * acc[ai][bj][m][n]; }
;             __builtin_amdgcn_sched_barrier(0);
;         }
; template <class Epi, class Sched>
; DI void gemm_phase(LAS unsigned char* lds, const Gemm g, const Sched& S, const Epi& E) {
;     ...
;         { int fr_e = fr, fq_e = fq; asm volatile("" : "+v"(fr_e), "+v"(fq_e)); E(acc, cur, wr, wc, fr_e, fq_e); } S.done(cur);
;         __builtin_amdgcn_s_waitcnt(0x0F70);
;         if (!has_next) break;
	v_pk_fma_f32 v[50:51], v[50:51], v[132:133], v[78:79]
	v_pk_fma_f32 v[48:49], v[48:49], v[130:131], v[76:77]
	global_store_dwordx4 v[154:155], v[48:51], off offset:576
	v_pk_fma_f32 v[34:35], v[34:35], v[132:133], v[94:95]
	v_pk_fma_f32 v[32:33], v[32:33], v[130:131], v[92:93]
	v_lshl_add_u64 v[48:49], v[152:153], 0, v[164:165]
	global_store_dwordx4 v[48:49], v[32:35], off offset:576
	v_pk_fma_f32 v[18:19], v[18:19], v[132:133], v[112:113]
	v_pk_fma_f32 v[16:17], v[16:17], v[130:131], v[110:111]
	v_lshl_add_u64 v[32:33], v[152:153], 0, v[168:169]
	v_pk_fma_f32 v[62:63], v[62:63], v[144:145], v[66:67]
	v_pk_fma_f32 v[60:61], v[60:61], v[142:143], v[64:65]
	v_pk_fma_f32 v[58:59], v[58:59], v[140:141], v[70:71]
	v_pk_fma_f32 v[56:57], v[56:57], v[138:139], v[68:69]
	v_pk_fma_f32 v[54:55], v[54:55], v[136:137], v[74:75]
	v_pk_fma_f32 v[52:53], v[52:53], v[134:135], v[72:73]
	v_pk_fma_f32 v[46:47], v[46:47], v[144:145], v[82:83]
	v_pk_fma_f32 v[44:45], v[44:45], v[142:143], v[80:81]
	v_pk_fma_f32 v[42:43], v[42:43], v[140:141], v[86:87]
	v_pk_fma_f32 v[40:41], v[40:41], v[138:139], v[84:85]
	v_pk_fma_f32 v[38:39], v[38:39], v[136:137], v[90:91]
	v_pk_fma_f32 v[36:37], v[36:37], v[134:135], v[88:89]
	v_pk_fma_f32 v[30:31], v[30:31], v[144:145], v[100:101]
	v_pk_fma_f32 v[28:29], v[28:29], v[142:143], v[98:99]
	v_pk_fma_f32 v[26:27], v[26:27], v[140:141], v[104:105]
	v_pk_fma_f32 v[24:25], v[24:25], v[138:139], v[102:103]
	v_pk_fma_f32 v[22:23], v[22:23], v[136:137], v[108:109]
	v_pk_fma_f32 v[20:21], v[20:21], v[134:135], v[106:107]
	global_store_dwordx4 v[32:33], v[16:19], off offset:576
	v_pk_fma_f32 v[14:15], v[14:15], v[144:145], v[116:117]
	v_pk_fma_f32 v[12:13], v[12:13], v[142:143], v[114:115]
	v_lshl_add_u64 v[16:17], v[152:153], 0, v[156:157]
	v_pk_fma_f32 v[10:11], v[10:11], v[140:141], v[120:121]
	v_pk_fma_f32 v[8:9], v[8:9], v[138:139], v[118:119]
	v_pk_fma_f32 v[6:7], v[6:7], v[136:137], v[124:125]
	v_pk_fma_f32 v[4:5], v[4:5], v[134:135], v[122:123]
	v_pk_fma_f32 v[2:3], v[2:3], v[132:133], v[128:129]
	v_pk_fma_f32 v[0:1], v[0:1], v[130:131], v[126:127]
	global_store_dwordx4 v[154:155], v[60:63], off
	global_store_dwordx4 v[154:155], v[56:59], off offset:64
	global_store_dwordx4 v[154:155], v[52:55], off offset:512
	global_store_dwordx4 v[48:49], v[44:47], off
	global_store_dwordx4 v[48:49], v[40:43], off offset:64
	global_store_dwordx4 v[48:49], v[36:39], off offset:512
	global_store_dwordx4 v[32:33], v[28:31], off
	global_store_dwordx4 v[32:33], v[24:27], off offset:64
	global_store_dwordx4 v[32:33], v[20:23], off offset:512
	global_store_dwordx4 v[16:17], v[12:15], off
	global_store_dwordx4 v[16:17], v[8:11], off offset:64
	global_store_dwordx4 v[16:17], v[4:7], off offset:512
	global_store_dwordx4 v[16:17], v[0:3], off offset:576
	s_and_b64 vcc, exec, s[42:43]
	s_mov_b32 s80, s30
	s_mov_b32 s10, s81
	s_mov_b64 s[74:75], s[46:47]
	s_mov_b64 s[82:83], s[44:45]
	s_cbranch_vccnz .LBB0_191

; template <class Epi, class Sched>
; DI void gemm_phase(LAS unsigned char* lds, const Gemm g, const Sched& S, const Epi& E) {
;     ...
;         { int fr_e = fr, fq_e = fq; asm volatile("" : "+v"(fr_e), "+v"(fq_e)); E(acc, cur, wr, wc, fr_e, fq_e); } S.done(cur);
;         __builtin_amdgcn_s_waitcnt(0x0F70);
;         if (!has_next) break;
.LBB0_302:
	s_and_b64 vcc, exec, s[42:43]
	s_mov_b32 s23, s51
	s_mov_b32 s22, s68
	s_mov_b64 s[82:83], s[4:5]
	s_mov_b64 s[48:49], s[36:37]
	s_cbranch_vccnz .LBB0_449

; DI unsigned pack2(float lo, float hi) { f32x2 v = {lo, hi}; return __builtin_bit_cast(unsigned, __builtin_convertvector(v, bf16x2_t)); }
;     DI void operator()(const f32x4 (&acc)[2][2][4][2], const Unit& u, int wr, int wc, int fr, int fq) const {
;     ...
;                 if (isc) { b = row >> 8; pos = row & 255; } else { b = (row - NCT) >> 11; pos = CTX + ((row - NCT) & 2047); }
;                 const int d0 = wc * 32 + 8 * fq;
;                 { const f32x4 v0 = acc[ai][0][m][0], v1 = acc[ai][0][m][1];
;                   u32x4 w; w.x = pack2(v0[0], v0[1]); w.y = pack2(v0[2], v0[3]); w.z = pack2(v1[0], v1[1]); w.w = pack2(v1[2], v1[3]);
;                   *(u32x4*)(K + ((size_t)(b * 4 + hh) * KP + pos) * 128 + d0) = w; }
;                 { const f32x4 v0 = acc[ai][1][m][0], v1 = acc[ai][1][m][1];
;                   bf16_t* vp = VT + (((size_t)(b * 4 + hh) * (KP / 64) + (pos >> 6)) * 128 + d0) * 64 + (pos & 63);
; #pragma unroll
;                   for (int j = 0; j < 4; ++j) { vp[j * 64] = (bf16_t)(pack2(v0[j], 0.f) & 0xffffu); vp[(4 + j) * 64] = (bf16_t)(pack2(v1[j], 0.f) & 0xffffu); } }
;                 __builtin_amdgcn_sched_barrier(0);
;             }
; template <class Epi, class Sched>
; DI void gemm_phase(LAS unsigned char* lds, const Gemm g, const Sched& S, const Epi& E) {
;     ...
;         { int fr_e = fr, fq_e = fq; asm volatile("" : "+v"(fr_e), "+v"(fq_e)); E(acc, cur, wr, wc, fr_e, fq_e); } S.done(cur);
;         __builtin_amdgcn_s_waitcnt(0x0F70);
;         if (!has_next) break;
.LBB0_622:
	v_cvt_pk_bf16_f32 v12, v12, v13
	v_cvt_pk_bf16_f32 v13, v14, v15
	v_cvt_pk_bf16_f32 v15, v10, v11
	v_lshl_add_u32 v10, v16, 2, s26
	v_cvt_pk_bf16_f32 v14, v8, v9
	v_mad_i64_i32 v[8:9], s[6:7], v10, s3, v[96:97]
	v_lshlrev_b64 v[8:9], 8, v[8:9]
	v_lshl_add_u64 v[8:9], s[50:51], 0, v[8:9]
	v_lshl_add_u64 v[8:9], v[144:145], 1, v[8:9]
	global_store_dwordx4 v[8:9], v[12:15], off
	v_lshrrev_b32_e32 v8, 6, v96
	v_mov_b32_e32 v9, v97
	v_mad_i64_i32 v[8:9], s[6:7], v10, 36, v[8:9]
	v_lshlrev_b64 v[8:9], 14, v[8:9]
	v_lshl_add_u64 v[8:9], s[52:53], 0, v[8:9]
	v_and_b32_e32 v10, 63, v96
	v_lshl_add_u64 v[8:9], v[8:9], 0, v[142:143]
	v_lshlrev_b32_e32 v96, 1, v10
	v_lshl_add_u64 v[8:9], v[8:9], 0, v[96:97]
	v_cvt_pk_bf16_f32 v0, v0, s0
	global_store_short v[8:9], v0, off offset:512
	v_cvt_pk_bf16_f32 v0, v5, s0
	global_store_short v[8:9], v0, off offset:128
	v_cvt_pk_bf16_f32 v0, v1, s0
	global_store_short v[8:9], v0, off offset:640
	v_cvt_pk_bf16_f32 v0, v6, s0
	global_store_short v[8:9], v0, off offset:256
	v_cvt_pk_bf16_f32 v0, v2, s0
	global_store_short v[8:9], v0, off offset:768
	v_cvt_pk_bf16_f32 v0, v7, s0
	v_cvt_pk_bf16_f32 v4, v4, s0
	global_store_short v[8:9], v0, off offset:384
	v_cvt_pk_bf16_f32 v0, v3, s0
	global_store_short v[8:9], v4, off
	global_store_short v[8:9], v0, off offset:896
	s_and_b64 vcc, exec, s[42:43]
	s_mov_b32 s26, s24
	s_mov_b32 s60, s41
	s_mov_b64 s[68:69], s[46:47]
	s_mov_b64 s[74:75], s[56:57]
	s_cbranch_vccnz .LBB0_668

; DI unsigned pack2(float lo, float hi) { f32x2 v = {lo, hi}; return __builtin_bit_cast(unsigned, __builtin_convertvector(v, bf16x2_t)); }
;     DI void operator()(const f32x4 (&acc)[2][2][4][2], const Unit& u, int wr, int wc, int fr, int fq) const {
;     ...
;                     bf16_t* qp = Q + ((size_t)(b * 4 + hh) * KP + pos) * 192 + within0 + 4 * fq;
;                     u32x2 w0, w1; w0.x = pack2(v0[0], v0[1]); w0.y = pack2(v0[2], v0[3]); w1.x = pack2(v1[0], v1[1]); w1.y = pack2(v1[2], v1[3]);
;                     *(u32x2*)(qp) = w0; *(u32x2*)(qp + 16) = w1;
;                 }
;                 __builtin_amdgcn_sched_barrier(0);
; template <class Epi, class Sched>
; DI void gemm_phase(LAS unsigned char* lds, const Gemm g, const Sched& S, const Epi& E) {
;     ...
;         { int fr_e = fr, fq_e = fq; asm volatile("" : "+v"(fr_e), "+v"(fq_e)); E(acc, cur, wr, wc, fr_e, fq_e); } S.done(cur);
;         __builtin_amdgcn_s_waitcnt(0x0F70);
;         if (!has_next) break;
.LBB0_681:
	v_add_u32_e32 v4, s30, v8
	v_mad_i64_i32 v[4:5], s[6:7], v4, s3, v[96:97]
	v_mov_b64_e32 v[6:7], s[52:53]
	v_mad_u64_u32 v[6:7], s[6:7], v4, s19, v[6:7]
	v_mad_i32_i24 v7, v5, s19, v7
	v_lshl_add_u64 v[4:5], s[84:85], 1, v[6:7]
	v_lshl_add_u64 v[4:5], v[64:65], 1, v[4:5]
	v_cvt_pk_bf16_f32 v0, v0, v1
	v_cvt_pk_bf16_f32 v1, v2, v3
	v_cvt_pk_bf16_f32 v2, v56, v57
	v_cvt_pk_bf16_f32 v3, v58, v59
	global_store_dwordx2 v[4:5], v[0:1], off
	global_store_dwordx2 v[4:5], v[2:3], off offset:32
	s_and_b64 vcc, exec, s[42:43]
	s_mov_b32 s84, s26
	s_mov_b32 s73, s27
	s_mov_b64 s[48:49], s[74:75]
	s_mov_b64 s[82:83], s[68:69]
	s_cbranch_vccnz .LBB0_760

; DI unsigned cvt_pk_bf16(float lo, float hi) { return pack2(lo, hi); }
;     DI void operator()(const f32x4 (&acc)[2][2][4][2], const Unit& u, int wr, int wc, int fr, int fq) const {
;         const int row0 = u.pm * BM + row_off + wr * 64 + fr; const int col0 = u.pn * BM + wc * 32 + 8 * fq;
; #pragma unroll
;         for (int ai = 0; ai < 2; ++ai)
; #pragma unroll
;             for (int m = 0; m < 4; ++m) { bf16_t* rowp = O + (size_t)(row0 + ai * HALF + m * 16) * ldc + col0;
; #pragma unroll
;                 for (int bj = 0; bj < 2; ++bj) { f32x4 v0 = acc[ai][bj][m][0], v1 = acc[ai][bj][m][1];
;                     if (ACT == 3) {
; #pragma unroll
;                         for (int j = 0; j < 4; ++j) { float a = fmaxf(v0[j], 0.f), b = fmaxf(v1[j], 0.f); v0[j] = a * a; v1[j] = b * b; } }
;                     u32x4 w; w.x = cvt_pk_bf16(v0[0], v0[1]); w.y = cvt_pk_bf16(v0[2], v0[3]); w.z = cvt_pk_bf16(v1[0], v1[1]); w.w = cvt_pk_bf16(v1[2], v1[3]);
;                     *(u32x4*)(rowp + bj * HALF) = w; } }
; template <class Epi, class Sched>
; DI void gemm_phase(LAS unsigned char* lds, const Gemm g, const Sched& S, const Epi& E) {
;     ...
;         { int fr_e = fr, fq_e = fq; asm volatile("" : "+v"(fr_e), "+v"(fq_e)); E(acc, cur, wr, wc, fr_e, fq_e); } S.done(cur);
;         __builtin_amdgcn_s_waitcnt(0x0F70);
;         if (!has_next) break;
.LBB0_771:
	s_lshl_b32 s6, s31, 8
	v_mov_b32_e32 v144, v140
	v_mov_b32_e32 v145, v141
	s_add_i32 s6, s83, s6
	s_lshl_b32 s7, s30, 8
	v_add_u32_e32 v146, s6, v145
	s_or_b32 s7, s7, s78
	v_ashrrev_i32_e32 v147, 31, v146
	v_lshl_add_u32 v144, v144, 3, s7
	v_lshlrev_b64 v[146:147], 12, v[146:147]
	v_ashrrev_i32_e32 v145, 31, v144
	v_lshl_add_u64 v[146:147], s[50:51], 0, v[146:147]
	v_lshl_add_u64 v[144:145], v[144:145], 1, v[146:147]
	s_mov_b64 s[6:7], 0x10000
	v_cvt_pk_bf16_f32 v118, v118, v119
	v_cvt_pk_bf16_f32 v119, v120, v121
	v_cvt_pk_bf16_f32 v120, v114, v115
	v_lshl_add_u64 v[114:115], v[144:145], 0, s[6:7]
	s_mov_b32 s6, 0x10000
	v_cvt_pk_bf16_f32 v110, v110, v111
	v_cvt_pk_bf16_f32 v111, v112, v113
	v_cvt_pk_bf16_f32 v112, v106, v107
	v_add_co_u32_e32 v106, vcc, s6, v144
	s_mov_b64 s[6:7], 0x20000
	s_nop 0
	v_addc_co_u32_e32 v107, vcc, 0, v145, vcc
	s_mov_b32 s3, 0x20000
	v_cvt_pk_bf16_f32 v102, v102, v103
	v_cvt_pk_bf16_f32 v103, v104, v105
	v_cvt_pk_bf16_f32 v104, v98, v99
	v_lshl_add_u64 v[98:99], v[144:145], 0, s[6:7]
	v_cvt_pk_bf16_f32 v92, v92, v93
	v_cvt_pk_bf16_f32 v93, v94, v95
	v_cvt_pk_bf16_f32 v94, v88, v89
	v_add_co_u32_e32 v88, vcc, s3, v144
	s_mov_b64 s[6:7], 0x30000
	s_nop 0
	v_addc_co_u32_e32 v89, vcc, 0, v145, vcc
	v_cvt_pk_bf16_f32 v84, v84, v85
	v_cvt_pk_bf16_f32 v85, v86, v87
	v_cvt_pk_bf16_f32 v86, v80, v81
	v_lshl_add_u64 v[80:81], v[144:145], 0, s[6:7]
	s_mov_b32 s6, 0x30000
	v_cvt_pk_bf16_f32 v76, v76, v77
	v_cvt_pk_bf16_f32 v77, v78, v79
	v_cvt_pk_bf16_f32 v78, v72, v73
	v_add_co_u32_e32 v72, vcc, s6, v144
	s_mov_b64 s[6:7], 0x80000
	s_nop 0
	v_addc_co_u32_e32 v73, vcc, 0, v145, vcc
	v_cvt_pk_bf16_f32 v68, v68, v69
	v_cvt_pk_bf16_f32 v69, v70, v71
	v_cvt_pk_bf16_f32 v70, v64, v65
	v_lshl_add_u64 v[64:65], v[144:145], 0, s[6:7]
	s_mov_b32 s6, 0x80000
	v_cvt_pk_bf16_f32 v60, v60, v61
	v_cvt_pk_bf16_f32 v61, v62, v63
	v_cvt_pk_bf16_f32 v62, v56, v57
	v_add_co_u32_e32 v56, vcc, s6, v144
	s_mov_b64 s[6:7], 0x90000
	s_nop 0
	v_addc_co_u32_e32 v57, vcc, 0, v145, vcc
	v_cvt_pk_bf16_f32 v52, v52, v53
	v_cvt_pk_bf16_f32 v53, v54, v55
	v_cvt_pk_bf16_f32 v54, v48, v49
	v_lshl_add_u64 v[48:49], v[144:145], 0, s[6:7]
	s_mov_b32 s6, 0x90000
	v_cvt_pk_bf16_f32 v44, v44, v45
	v_cvt_pk_bf16_f32 v45, v46, v47
	v_cvt_pk_bf16_f32 v46, v40, v41
	v_add_co_u32_e32 v40, vcc, s6, v144
	s_mov_b64 s[6:7], 0xa0000
	s_nop 0
	v_addc_co_u32_e32 v41, vcc, 0, v145, vcc
	v_cvt_pk_bf16_f32 v36, v36, v37
	v_cvt_pk_bf16_f32 v37, v38, v39
	v_cvt_pk_bf16_f32 v38, v32, v33
	v_lshl_add_u64 v[32:33], v[144:145], 0, s[6:7]
	s_mov_b32 s6, 0xa0000
	v_cvt_pk_bf16_f32 v28, v28, v29
	v_cvt_pk_bf16_f32 v29, v30, v31
	v_cvt_pk_bf16_f32 v30, v24, v25
	v_add_co_u32_e32 v24, vcc, s6, v144
	s_mov_b64 s[6:7], 0xb0000
	s_nop 0
	v_addc_co_u32_e32 v25, vcc, 0, v145, vcc
	v_cvt_pk_bf16_f32 v20, v20, v21
	v_cvt_pk_bf16_f32 v21, v22, v23
	v_cvt_pk_bf16_f32 v22, v16, v17
	v_lshl_add_u64 v[16:17], v[144:145], 0, s[6:7]
	s_mov_b32 s6, 0xb0000
	v_cvt_pk_bf16_f32 v12, v12, v13
	v_cvt_pk_bf16_f32 v13, v14, v15
	v_cvt_pk_bf16_f32 v14, v8, v9
	v_add_co_u32_e32 v8, vcc, s6, v144
	v_cvt_pk_bf16_f32 v122, v122, v123
	s_nop 0
	v_addc_co_u32_e32 v9, vcc, 0, v145, vcc
	v_cvt_pk_bf16_f32 v123, v124, v125
	v_cvt_pk_bf16_f32 v124, v126, v127
	v_cvt_pk_bf16_f32 v125, v128, v129
	v_cvt_pk_bf16_f32 v121, v116, v117
	v_cvt_pk_bf16_f32 v113, v108, v109
	v_cvt_pk_bf16_f32 v105, v100, v101
	v_cvt_pk_bf16_f32 v95, v90, v91
	v_cvt_pk_bf16_f32 v87, v82, v83
	v_cvt_pk_bf16_f32 v79, v74, v75
	v_cvt_pk_bf16_f32 v71, v66, v67
	v_cvt_pk_bf16_f32 v63, v58, v59
	v_cvt_pk_bf16_f32 v55, v50, v51
	v_cvt_pk_bf16_f32 v47, v42, v43
	v_cvt_pk_bf16_f32 v39, v34, v35
	v_cvt_pk_bf16_f32 v31, v26, v27
	v_cvt_pk_bf16_f32 v23, v18, v19
	v_cvt_pk_bf16_f32 v15, v10, v11
	v_cvt_pk_bf16_f32 v4, v4, v5
	v_cvt_pk_bf16_f32 v5, v6, v7
	v_cvt_pk_bf16_f32 v6, v0, v1
	v_cvt_pk_bf16_f32 v7, v2, v3
	s_and_b64 vcc, exec, s[42:43]
	s_mov_b32 s30, s85
	s_mov_b32 s31, s86
	s_mov_b64 s[54:55], s[46:47]
	s_mov_b64 s[56:57], s[44:45]
	global_store_dwordx4 v[144:145], v[122:125], off
	global_store_dwordx4 v[144:145], v[118:121], off offset:256
	global_store_dwordx4 v[106:107], v[110:113], off
	global_store_dwordx4 v[114:115], v[102:105], off offset:256
	global_store_dwordx4 v[88:89], v[92:95], off
	global_store_dwordx4 v[98:99], v[84:87], off offset:256
	global_store_dwordx4 v[72:73], v[76:79], off
	global_store_dwordx4 v[80:81], v[68:71], off offset:256
	global_store_dwordx4 v[56:57], v[60:63], off
	global_store_dwordx4 v[64:65], v[52:55], off offset:256
	global_store_dwordx4 v[40:41], v[44:47], off
	global_store_dwordx4 v[48:49], v[36:39], off offset:256
	global_store_dwordx4 v[24:25], v[28:31], off
	global_store_dwordx4 v[32:33], v[20:23], off offset:256
	global_store_dwordx4 v[8:9], v[12:15], off
	global_store_dwordx4 v[16:17], v[4:7], off offset:256
	s_cbranch_vccnz .LBB0_1090

; DI unsigned cvt_pk_bf16(float lo, float hi) { return pack2(lo, hi); }
;     DI void operator()(const f32x4 (&acc)[2][2][4][2], const Unit& u, int wr, int wc, int fr, int fq) const {
;         const int row0 = u.pm * BM + row_off + wr * 64 + fr; const int col0 = u.pn * BM + wc * 32 + 8 * fq;
; #pragma unroll
;         for (int ai = 0; ai < 2; ++ai)
; #pragma unroll
;             for (int m = 0; m < 4; ++m) { bf16_t* rowp = O + (size_t)(row0 + ai * HALF + m * 16) * ldc + col0;
; #pragma unroll
;                 for (int bj = 0; bj < 2; ++bj) { f32x4 v0 = acc[ai][bj][m][0], v1 = acc[ai][bj][m][1];
;                     if (ACT == 3) {
; #pragma unroll
;                         for (int j = 0; j < 4; ++j) { float a = fmaxf(v0[j], 0.f), b = fmaxf(v1[j], 0.f); v0[j] = a * a; v1[j] = b * b; } }
;                     u32x4 w; w.x = cvt_pk_bf16(v0[0], v0[1]); w.y = cvt_pk_bf16(v0[2], v0[3]); w.z = cvt_pk_bf16(v1[0], v1[1]); w.w = cvt_pk_bf16(v1[2], v1[3]);
;                     *(u32x4*)(rowp + bj * HALF) = w; } }
; template <class Epi, class Sched>
; DI void gemm_phase(LAS unsigned char* lds, const Gemm g, const Sched& S, const Epi& E) {
;     ...
;         { int fr_e = fr, fq_e = fq; asm volatile("" : "+v"(fr_e), "+v"(fq_e)); E(acc, cur, wr, wc, fr_e, fq_e); } S.done(cur);
;         __builtin_amdgcn_s_waitcnt(0x0F70);
;         if (!has_next) break;
.LBB0_969:
	v_mov_b32_e32 v144, v140
	v_mov_b32_e32 v145, v141
	s_lshl_b32 s6, s31, 8
	s_lshl_b32 s7, s30, 8
	s_or_b32 s7, s7, s77
	s_add_i32 s6, s6, s76
	v_lshl_add_u32 v144, v144, 3, s7
	v_add_u32_e32 v150, s6, v145
	v_ashrrev_i32_e32 v145, 31, v144
	v_mov_b64_e32 v[146:147], s[50:51]
	s_movk_i32 s3, 0x2600
	v_cvt_pk_bf16_f32 v118, v118, v119
	v_cvt_pk_bf16_f32 v119, v120, v121
	v_cvt_pk_bf16_f32 v120, v114, v115
	v_add_u32_e32 v114, 16, v150
	v_cvt_pk_bf16_f32 v102, v102, v103
	v_cvt_pk_bf16_f32 v103, v104, v105
	v_cvt_pk_bf16_f32 v104, v98, v99
	v_add_u32_e32 v98, 32, v150
	v_cvt_pk_bf16_f32 v84, v84, v85
	v_cvt_pk_bf16_f32 v85, v86, v87
	v_cvt_pk_bf16_f32 v86, v80, v81
	v_add_u32_e32 v80, 48, v150
	v_cvt_pk_bf16_f32 v68, v68, v69
	v_cvt_pk_bf16_f32 v69, v70, v71
	v_cvt_pk_bf16_f32 v70, v64, v65
	v_add_u32_e32 v64, 0x80, v150
	v_cvt_pk_bf16_f32 v52, v52, v53
	v_cvt_pk_bf16_f32 v53, v54, v55
	v_cvt_pk_bf16_f32 v54, v48, v49
	v_add_u32_e32 v48, 0x90, v150
	v_cvt_pk_bf16_f32 v36, v36, v37
	v_cvt_pk_bf16_f32 v37, v38, v39
	v_cvt_pk_bf16_f32 v38, v32, v33
	v_add_u32_e32 v32, 0xa0, v150
	v_cvt_pk_bf16_f32 v20, v20, v21
	v_cvt_pk_bf16_f32 v21, v22, v23
	v_cvt_pk_bf16_f32 v22, v16, v17
	v_add_u32_e32 v16, 0xb0, v150
	v_mad_i64_i32 v[148:149], s[6:7], v150, s3, v[146:147]
	v_lshlrev_b64 v[144:145], 1, v[144:145]
	v_mad_i64_i32 v[114:115], s[6:7], v114, s3, v[146:147]
	v_mad_i64_i32 v[98:99], s[6:7], v98, s3, v[146:147]
	v_mad_i64_i32 v[80:81], s[6:7], v80, s3, v[146:147]
	v_mad_i64_i32 v[64:65], s[6:7], v64, s3, v[146:147]
	v_mad_i64_i32 v[48:49], s[6:7], v48, s3, v[146:147]
	v_mad_i64_i32 v[32:33], s[6:7], v32, s3, v[146:147]
	v_mad_i64_i32 v[16:17], s[6:7], v16, s3, v[146:147]
	v_lshl_add_u64 v[148:149], v[148:149], 0, v[144:145]
	v_cvt_pk_bf16_f32 v122, v122, v123
	v_cvt_pk_bf16_f32 v123, v124, v125
	v_cvt_pk_bf16_f32 v124, v126, v127
	v_cvt_pk_bf16_f32 v125, v128, v129
	v_cvt_pk_bf16_f32 v121, v116, v117
	v_lshl_add_u64 v[114:115], v[114:115], 0, v[144:145]
	v_cvt_pk_bf16_f32 v110, v110, v111
	v_cvt_pk_bf16_f32 v111, v112, v113
	v_cvt_pk_bf16_f32 v112, v106, v107
	v_cvt_pk_bf16_f32 v113, v108, v109
	v_cvt_pk_bf16_f32 v105, v100, v101
	v_lshl_add_u64 v[98:99], v[98:99], 0, v[144:145]
	v_cvt_pk_bf16_f32 v92, v92, v93
	v_cvt_pk_bf16_f32 v93, v94, v95
	v_cvt_pk_bf16_f32 v94, v88, v89
	v_cvt_pk_bf16_f32 v95, v90, v91
	v_cvt_pk_bf16_f32 v87, v82, v83
	v_lshl_add_u64 v[80:81], v[80:81], 0, v[144:145]
	v_cvt_pk_bf16_f32 v76, v76, v77
	v_cvt_pk_bf16_f32 v77, v78, v79
	v_cvt_pk_bf16_f32 v78, v72, v73
	v_cvt_pk_bf16_f32 v79, v74, v75
	v_cvt_pk_bf16_f32 v71, v66, v67
	v_lshl_add_u64 v[64:65], v[64:65], 0, v[144:145]
	v_cvt_pk_bf16_f32 v60, v60, v61
	v_cvt_pk_bf16_f32 v61, v62, v63
	v_cvt_pk_bf16_f32 v62, v56, v57
	v_cvt_pk_bf16_f32 v63, v58, v59
	v_cvt_pk_bf16_f32 v55, v50, v51
	v_lshl_add_u64 v[48:49], v[48:49], 0, v[144:145]
	v_cvt_pk_bf16_f32 v44, v44, v45
	v_cvt_pk_bf16_f32 v45, v46, v47
	v_cvt_pk_bf16_f32 v46, v40, v41
	v_cvt_pk_bf16_f32 v47, v42, v43
	v_cvt_pk_bf16_f32 v39, v34, v35
	v_lshl_add_u64 v[32:33], v[32:33], 0, v[144:145]
	v_cvt_pk_bf16_f32 v28, v28, v29
	v_cvt_pk_bf16_f32 v29, v30, v31
	v_cvt_pk_bf16_f32 v30, v24, v25
	v_cvt_pk_bf16_f32 v31, v26, v27
	v_cvt_pk_bf16_f32 v23, v18, v19
	v_lshl_add_u64 v[16:17], v[16:17], 0, v[144:145]
	v_cvt_pk_bf16_f32 v12, v12, v13
	v_cvt_pk_bf16_f32 v13, v14, v15
	v_cvt_pk_bf16_f32 v14, v8, v9
	v_cvt_pk_bf16_f32 v15, v10, v11
	v_cvt_pk_bf16_f32 v4, v4, v5
	v_cvt_pk_bf16_f32 v5, v6, v7
	v_cvt_pk_bf16_f32 v6, v0, v1
	v_cvt_pk_bf16_f32 v7, v2, v3
	s_and_b64 vcc, exec, s[42:43]
	s_mov_b32 s30, s83
	s_mov_b32 s31, s84
	s_mov_b64 s[54:55], s[46:47]
	s_mov_b64 s[56:57], s[44:45]
	global_store_dwordx4 v[148:149], v[122:125], off
	global_store_dwordx4 v[148:149], v[118:121], off offset:256
	global_store_dwordx4 v[114:115], v[110:113], off
	global_store_dwordx4 v[114:115], v[102:105], off offset:256
	global_store_dwordx4 v[98:99], v[92:95], off
	global_store_dwordx4 v[98:99], v[84:87], off offset:256
	global_store_dwordx4 v[80:81], v[76:79], off
	global_store_dwordx4 v[80:81], v[68:71], off offset:256
	global_store_dwordx4 v[64:65], v[60:63], off
	global_store_dwordx4 v[64:65], v[52:55], off offset:256
	global_store_dwordx4 v[48:49], v[44:47], off
	global_store_dwordx4 v[48:49], v[36:39], off offset:256
	global_store_dwordx4 v[32:33], v[28:31], off
	global_store_dwordx4 v[32:33], v[20:23], off offset:256
	global_store_dwordx4 v[16:17], v[12:15], off
	global_store_dwordx4 v[16:17], v[4:7], off offset:256
	s_cbranch_vccnz .LBB0_983
